# residual quarter units: peeled first ring iteration with C=0 (no accumulator zeroing pass for quarter units); prologue transposes skip workgroups 0-31
# speedup vs baseline: 1.0035x; 1.0035x over previous
; #define PG8_STAGE(bufoff, gbase, voff) do { _Pragma("unroll") for (int _i = 0; _i < 2; ++_i) \
;         __builtin_amdgcn_global_load_lds((const unsigned*)((const char*)(gbase) + (voff)[_i]), (PG8_LAS unsigned*)(lds + (bufoff) + ldsw + _i * 8192), 16, 0, 0); } while (0)
; #define PG8_LDA(dst, b, h) do { _Pragma("unroll") for (int m = 0; m < 4; ++m) _Pragma("unroll") for (int k = 0; k < 2; ++k) dst[m][k] = *(const PG8_LAS bf16x8*)(lds + PG8_SA(b, h) + aoff + m * 2048 + k * 1024); } while (0)
; #define PG8_LDB(dst, b, h) do { _Pragma("unroll") for (int n = 0; n < 2; ++n) _Pragma("unroll") for (int k = 0; k < 2; ++k) dst[n][k] = *(const PG8_LAS bf16x8*)(lds + PG8_SB(b, h) + boff + n * 2048 + k * 1024); } while (0)
; #define PG8_MMA(ai, bj, At, Bt) do { __builtin_amdgcn_s_setprio(1); _Pragma("unroll") for (int m = 0; m < 4; ++m) _Pragma("unroll") for (int n = 0; n < 2; ++n) _Pragma("unroll") for (int k = 0; k < 2; ++k) \
;         acc[ai][bj][m][n] = __builtin_amdgcn_mfma_f32_16x16x32_bf16(Bt[n][k], At[m][k], acc[ai][bj][m][n], 0, 0, 0); __builtin_amdgcn_s_setprio(0); } while (0)
; #define PG8_WAIT_V(n) asm volatile("s_waitcnt vmcnt(" #n ")" ::: "memory")
; #define PG8_WAIT_L(n) asm volatile("s_waitcnt lgkmcnt(" #n ")" ::: "memory")
; #define PG8_BAR __builtin_amdgcn_s_barrier()
; #define PG8_SCHED __builtin_amdgcn_sched_barrier(0)
; template <class Epi, class Sched, bool ALIGN_EPI = false, bool SP2 = false>
; __device__ __forceinline__ void gemm_phase(PG8_LAS unsigned char* lds, const Gemm g, const Sched& S, const Epi& E) {
;     ...
;             PG8_LDB(B0, 0, 0); PG8_LDB(B1, 0, 1); PG8_SCHED; PG8_LDA(At, 0, 0); PG8_STAGE(PG8_SA(1, 1), a1 + hstep, voffA);
;             PG8_WAIT_V(8); PG8_WAIT_L(0); PG8_BAR; PG8_MMA(0, 0, At, B0); PG8_MMA(0, 1, At, B1); PG8_BAR; PG8_SCHED;
;             PG8_LDA(At, 0, 1); PG8_STAGE(PG8_SB(0, 0), b2, voffB); PG8_STAGE(PG8_SB(0, 1), b2 + hstep, voffB); PG8_STAGE(PG8_SA(0, 0), a2, voffA);
;     ...
;         for (int a = 0; a < 2; ++a)
; #pragma unroll
;             for (int b = 0; b < 2; ++b)
; #pragma unroll
;                 for (int m = 0; m < 4; ++m)
; #pragma unroll
;                     for (int n = 0; n < 2; ++n) acc[a][b][m][n] = (f32x4){0.f, 0.f, 0.f, 0.f};
.LBB0_848:
	s_add_u32 s48, s48, 0x80
	s_addc_u32 s49, s49, 0
	s_add_u32 s80, s76, 0x100
	v_mov_b32_e32 v2, 0
	s_addc_u32 s81, s77, 0
	s_mov_b32 s76, 0
	s_and_b32 s98, s101, 7
	s_cmp_lg_u32 s98, 0
	s_cbranch_scc0 .Lpeel_r
	s_and_b32 s98, s101, 7
	s_cmp_eq_u32 s98, 1
	s_cbranch_scc1 .Lkq_1
	s_and_b32 s98, s101, 7
	s_cmp_eq_u32 s98, 2
	s_cbranch_scc1 .Lkq_2
	s_and_b32 s98, s101, 7
	s_cmp_eq_u32 s98, 3
	s_cbranch_scc1 .Lkq_3
	s_branch .Lkq_4
.Lpeel_r:
	s_add_i32 s82, s76, 2
	s_add_u32 s83, s48, 0x80
	s_addc_u32 s77, s49, 0
	s_add_i32 s59, 0, 0x10000
	s_cmp_eq_u32 s72, s76
	s_cselect_b32 s77, s9, s77
	s_cselect_b32 s76, s8, s83
	v_add_u32_e32 v136, s59, v147
	s_cselect_b32 vcc_hi, s47, s81
	s_cselect_b32 vcc_lo, s46, s80
	s_add_i32 s83, 0, 0x14000
	ds_read_b128 v[148:151], v136
	ds_read_b128 v[152:155], v136 offset:1024
	ds_read_b128 v[156:159], v136 offset:2048
	ds_read_b128 v[160:163], v136 offset:3072
	v_add_u32_e32 v136, s83, v147
	ds_read_b128 v[166:169], v136
	ds_read_b128 v[170:173], v136 offset:1024
	ds_read_b128 v[174:177], v136 offset:2048
	ds_read_b128 v[178:181], v136 offset:3072
	v_lshl_add_u64 v[136:137], s[48:49], 0, v[132:133]
	s_add_i32 m0, s94, 0xc000
	ds_read_b128 v[202:205], v165
	ds_read_b128 v[208:211], v165 offset:1024
	ds_read_b128 v[212:215], v165 offset:2048
	ds_read_b128 v[216:219], v165 offset:3072
	ds_read_b128 v[220:223], v165 offset:4096
	ds_read_b128 v[224:227], v165 offset:5120
	ds_read_b128 v[228:231], v165 offset:6144
	ds_read_b128 v[232:235], v165 offset:7168
	global_load_lds_dwordx4 v[136:137], off
	v_lshl_add_u64 v[136:137], s[48:49], 0, v[134:135]
	s_add_i32 m0, s94, 0xe000
	s_nop 0
	global_load_lds_dwordx4 v[136:137], off
	s_waitcnt vmcnt(8)
	s_waitcnt lgkmcnt(0)
	s_barrier
	s_setprio 1
	s_waitcnt lgkmcnt(0)
	v_mfma_f32_16x16x32_bf16 v[126:129], v[148:151], v[202:205], 0
	v_mfma_f32_16x16x32_bf16 v[122:125], v[156:159], v[202:205], 0
	v_mfma_f32_16x16x32_bf16 v[110:113], v[148:151], v[212:215], 0
	v_mfma_f32_16x16x32_bf16 v[106:109], v[156:159], v[212:215], 0
	v_mfma_f32_16x16x32_bf16 v[94:97], v[148:151], v[220:223], 0
	v_mfma_f32_16x16x32_bf16 v[90:93], v[156:159], v[220:223], 0
	v_mfma_f32_16x16x32_bf16 v[78:81], v[148:151], v[228:231], 0
	v_mfma_f32_16x16x32_bf16 v[74:77], v[156:159], v[228:231], 0
	v_mfma_f32_16x16x32_bf16 v[126:129], v[152:155], v[208:211], v[126:129]
	v_mfma_f32_16x16x32_bf16 v[122:125], v[160:163], v[208:211], v[122:125]
	v_mfma_f32_16x16x32_bf16 v[110:113], v[152:155], v[216:219], v[110:113]
	v_mfma_f32_16x16x32_bf16 v[106:109], v[160:163], v[216:219], v[106:109]
	v_mfma_f32_16x16x32_bf16 v[94:97], v[152:155], v[224:227], v[94:97]
	v_mfma_f32_16x16x32_bf16 v[90:93], v[160:163], v[224:227], v[90:93]
	v_mfma_f32_16x16x32_bf16 v[78:81], v[152:155], v[232:235], v[78:81]
	v_mfma_f32_16x16x32_bf16 v[74:77], v[160:163], v[232:235], v[74:77]
	s_setprio 0
	s_setprio 1
	v_mfma_f32_16x16x32_bf16 v[118:121], v[166:169], v[202:205], 0
	v_mfma_f32_16x16x32_bf16 v[114:117], v[174:177], v[202:205], 0
	v_mfma_f32_16x16x32_bf16 v[102:105], v[166:169], v[212:215], 0
	v_mfma_f32_16x16x32_bf16 v[98:101], v[174:177], v[212:215], 0
	v_mfma_f32_16x16x32_bf16 v[86:89], v[166:169], v[220:223], 0
	v_mfma_f32_16x16x32_bf16 v[82:85], v[174:177], v[220:223], 0
	v_mfma_f32_16x16x32_bf16 v[70:73], v[166:169], v[228:231], 0
	v_mfma_f32_16x16x32_bf16 v[66:69], v[174:177], v[228:231], 0
	v_mfma_f32_16x16x32_bf16 v[118:121], v[170:173], v[208:211], v[118:121]
	v_mfma_f32_16x16x32_bf16 v[114:117], v[178:181], v[208:211], v[114:117]
	v_mfma_f32_16x16x32_bf16 v[102:105], v[170:173], v[216:219], v[102:105]
	v_mfma_f32_16x16x32_bf16 v[98:101], v[178:181], v[216:219], v[98:101]
	v_mfma_f32_16x16x32_bf16 v[86:89], v[170:173], v[224:227], v[86:89]
	v_mfma_f32_16x16x32_bf16 v[82:85], v[178:181], v[224:227], v[82:85]
	v_mfma_f32_16x16x32_bf16 v[70:73], v[170:173], v[232:235], v[70:73]
	v_mfma_f32_16x16x32_bf16 v[66:69], v[178:181], v[232:235], v[66:69]
	s_setprio 0
	s_barrier
	s_add_i32 s59, s59, s93
	v_lshl_add_u64 v[136:137], vcc, 0, v[0:1]
	s_mov_b32 m0, s59
	ds_read_b128 v[202:205], v165 offset:16384
	ds_read_b128 v[208:211], v165 offset:17408
	ds_read_b128 v[212:215], v165 offset:18432
	ds_read_b128 v[216:219], v165 offset:19456
	ds_read_b128 v[220:223], v165 offset:20480
	ds_read_b128 v[224:227], v165 offset:21504
	ds_read_b128 v[228:231], v165 offset:22528
	ds_read_b128 v[232:235], v165 offset:23552
	global_load_lds_dwordx4 v[136:137], off
	s_add_i32 m0, s59, 0x2000
	v_lshl_add_u64 v[144:145], vcc, 0, v[130:131]
	s_add_u32 vcc_lo, vcc_lo, s10
	s_addc_u32 vcc_hi, vcc_hi, 0
	s_add_i32 s59, s83, s93
	global_load_lds_dwordx4 v[144:145], off
	v_lshl_add_u64 v[182:183], vcc, 0, v[0:1]
	s_mov_b32 m0, s59
	v_lshl_add_u64 v[236:237], vcc, 0, v[130:131]
	global_load_lds_dwordx4 v[182:183], off
	s_add_i32 m0, s59, 0x2000
	v_lshl_add_u64 v[238:239], s[76:77], 0, v[0:1]
	global_load_lds_dwordx4 v[236:237], off
	s_mov_b32 m0, s94
	v_lshl_add_u64 v[240:241], s[76:77], 0, v[130:131]
	global_load_lds_dwordx4 v[238:239], off
	s_mov_b32 m0, s95
	s_nop 0
	global_load_lds_dwordx4 v[240:241], off
	s_waitcnt vmcnt(8)
	s_waitcnt lgkmcnt(0)
	s_barrier
; #define PG8_STAGE(bufoff, gbase, voff) do { _Pragma("unroll") for (int _i = 0; _i < 2; ++_i) \
;         __builtin_amdgcn_global_load_lds((const unsigned*)((const char*)(gbase) + (voff)[_i]), (PG8_LAS unsigned*)(lds + (bufoff) + ldsw + _i * 8192), 16, 0, 0); } while (0)
; #define PG8_LDA(dst, b, h) do { _Pragma("unroll") for (int m = 0; m < 4; ++m) _Pragma("unroll") for (int k = 0; k < 2; ++k) dst[m][k] = *(const PG8_LAS bf16x8*)(lds + PG8_SA(b, h) + aoff + m * 2048 + k * 1024); } while (0)
; #define PG8_LDB(dst, b, h) do { _Pragma("unroll") for (int n = 0; n < 2; ++n) _Pragma("unroll") for (int k = 0; k < 2; ++k) dst[n][k] = *(const PG8_LAS bf16x8*)(lds + PG8_SB(b, h) + boff + n * 2048 + k * 1024); } while (0)
; #define PG8_MMA(ai, bj, At, Bt) do { __builtin_amdgcn_s_setprio(1); _Pragma("unroll") for (int m = 0; m < 4; ++m) _Pragma("unroll") for (int n = 0; n < 2; ++n) _Pragma("unroll") for (int k = 0; k < 2; ++k) \
;         acc[ai][bj][m][n] = __builtin_amdgcn_mfma_f32_16x16x32_bf16(Bt[n][k], At[m][k], acc[ai][bj][m][n], 0, 0, 0); __builtin_amdgcn_s_setprio(0); } while (0)
; #define PG8_WAIT_V(n) asm volatile("s_waitcnt vmcnt(" #n ")" ::: "memory")
; #define PG8_WAIT_L(n) asm volatile("s_waitcnt lgkmcnt(" #n ")" ::: "memory")
; #define PG8_BAR __builtin_amdgcn_s_barrier()
; #define PG8_SCHED __builtin_amdgcn_sched_barrier(0)
; template <class Epi, class Sched, bool ALIGN_EPI = false, bool SP2 = false>
; __device__ __forceinline__ void gemm_phase(PG8_LAS unsigned char* lds, const Gemm g, const Sched& S, const Epi& E) {
;     ...
;             PG8_WAIT_V(8); PG8_WAIT_L(0); PG8_BAR; PG8_MMA(1, 0, At, B0); PG8_MMA(1, 1, At, B1); PG8_BAR; PG8_SCHED;
;             PG8_LDB(B0, 1, 0); PG8_LDB(B1, 1, 1); PG8_SCHED; PG8_LDA(At, 1, 0); PG8_STAGE(PG8_SA(0, 1), a2 + hstep, voffA);
;             PG8_WAIT_V(8); PG8_WAIT_L(0); PG8_BAR; PG8_MMA(0, 0, At, B0); PG8_MMA(0, 1, At, B1); PG8_BAR; PG8_SCHED;
	s_setprio 1
	s_waitcnt lgkmcnt(0)
	v_mfma_f32_16x16x32_bf16 v[62:65], v[148:151], v[202:205], 0
	v_mfma_f32_16x16x32_bf16 v[58:61], v[156:159], v[202:205], 0
	v_mfma_f32_16x16x32_bf16 v[46:49], v[148:151], v[212:215], 0
	v_mfma_f32_16x16x32_bf16 v[42:45], v[156:159], v[212:215], 0
	v_mfma_f32_16x16x32_bf16 v[30:33], v[148:151], v[220:223], 0
	v_mfma_f32_16x16x32_bf16 v[26:29], v[156:159], v[220:223], 0
	v_mfma_f32_16x16x32_bf16 v[14:17], v[148:151], v[228:231], 0
	v_mfma_f32_16x16x32_bf16 v[10:13], v[156:159], v[228:231], 0
	v_mfma_f32_16x16x32_bf16 v[62:65], v[152:155], v[208:211], v[62:65]
	v_mfma_f32_16x16x32_bf16 v[58:61], v[160:163], v[208:211], v[58:61]
	v_mfma_f32_16x16x32_bf16 v[46:49], v[152:155], v[216:219], v[46:49]
	v_mfma_f32_16x16x32_bf16 v[42:45], v[160:163], v[216:219], v[42:45]
	v_mfma_f32_16x16x32_bf16 v[30:33], v[152:155], v[224:227], v[30:33]
	v_mfma_f32_16x16x32_bf16 v[26:29], v[160:163], v[224:227], v[26:29]
	v_mfma_f32_16x16x32_bf16 v[14:17], v[152:155], v[232:235], v[14:17]
	v_mfma_f32_16x16x32_bf16 v[10:13], v[160:163], v[232:235], v[10:13]
	s_setprio 0
	s_setprio 1
	v_mfma_f32_16x16x32_bf16 v[54:57], v[166:169], v[202:205], 0
	v_mfma_f32_16x16x32_bf16 v[50:53], v[174:177], v[202:205], 0
	v_mfma_f32_16x16x32_bf16 v[38:41], v[166:169], v[212:215], 0
	v_mfma_f32_16x16x32_bf16 v[34:37], v[174:177], v[212:215], 0
	v_mfma_f32_16x16x32_bf16 v[22:25], v[166:169], v[220:223], 0
	v_mfma_f32_16x16x32_bf16 v[18:21], v[174:177], v[220:223], 0
	v_mfma_f32_16x16x32_bf16 v[6:9], v[166:169], v[228:231], 0
	v_mfma_f32_16x16x32_bf16 v[2:5], v[174:177], v[228:231], 0
	v_mfma_f32_16x16x32_bf16 v[54:57], v[170:173], v[208:211], v[54:57]
	v_mfma_f32_16x16x32_bf16 v[50:53], v[178:181], v[208:211], v[50:53]
	v_mfma_f32_16x16x32_bf16 v[38:41], v[170:173], v[216:219], v[38:41]
	v_mfma_f32_16x16x32_bf16 v[34:37], v[178:181], v[216:219], v[34:37]
	v_mfma_f32_16x16x32_bf16 v[22:25], v[170:173], v[224:227], v[22:25]
	v_mfma_f32_16x16x32_bf16 v[18:21], v[178:181], v[224:227], v[18:21]
	v_mfma_f32_16x16x32_bf16 v[6:9], v[170:173], v[232:235], v[6:9]
	v_mfma_f32_16x16x32_bf16 v[2:5], v[178:181], v[232:235], v[2:5]
	s_setprio 0
	s_barrier
	s_add_i32 s59, 0, 0x18000
	s_add_i32 s83, 0, 0x1c000
	v_add_u32_e32 v160, s59, v147
	v_add_u32_e32 v178, s83, v147
	ds_read_b128 v[148:151], v160
	ds_read_b128 v[152:155], v160 offset:1024
	ds_read_b128 v[156:159], v160 offset:2048
	ds_read_b128 v[160:163], v160 offset:3072
	ds_read_b128 v[166:169], v178
	ds_read_b128 v[170:173], v178 offset:1024
	ds_read_b128 v[174:177], v178 offset:2048
	ds_read_b128 v[178:181], v178 offset:3072
	s_add_u32 s76, s76, s10
	s_addc_u32 s77, s77, 0
	s_mov_b32 m0, s84
	v_lshl_add_u64 v[242:243], s[76:77], 0, v[0:1]
	ds_read_b128 v[202:205], v165 offset:32768
	ds_read_b128 v[208:211], v165 offset:33792
	ds_read_b128 v[212:215], v165 offset:34816
	ds_read_b128 v[216:219], v165 offset:35840
	ds_read_b128 v[220:223], v165 offset:36864
	ds_read_b128 v[224:227], v165 offset:37888
	ds_read_b128 v[228:231], v165 offset:38912
	ds_read_b128 v[232:235], v165 offset:39936
	global_load_lds_dwordx4 v[242:243], off
	v_lshl_add_u64 v[242:243], s[76:77], 0, v[130:131]
	s_mov_b32 m0, s74
	s_nop 0
	global_load_lds_dwordx4 v[242:243], off
	s_waitcnt vmcnt(8)
	s_waitcnt lgkmcnt(0)
	s_barrier
	s_setprio 1
	s_waitcnt lgkmcnt(0)
	v_mfma_f32_16x16x32_bf16 v[126:129], v[148:151], v[202:205], v[126:129]
	v_mfma_f32_16x16x32_bf16 v[122:125], v[156:159], v[202:205], v[122:125]
	v_mfma_f32_16x16x32_bf16 v[110:113], v[148:151], v[212:215], v[110:113]
	v_mfma_f32_16x16x32_bf16 v[106:109], v[156:159], v[212:215], v[106:109]
	v_mfma_f32_16x16x32_bf16 v[94:97], v[148:151], v[220:223], v[94:97]
	v_mfma_f32_16x16x32_bf16 v[90:93], v[156:159], v[220:223], v[90:93]
	v_mfma_f32_16x16x32_bf16 v[78:81], v[148:151], v[228:231], v[78:81]
	v_mfma_f32_16x16x32_bf16 v[74:77], v[156:159], v[228:231], v[74:77]
	v_mfma_f32_16x16x32_bf16 v[126:129], v[152:155], v[208:211], v[126:129]
	v_mfma_f32_16x16x32_bf16 v[122:125], v[160:163], v[208:211], v[122:125]
	v_mfma_f32_16x16x32_bf16 v[110:113], v[152:155], v[216:219], v[110:113]
	v_mfma_f32_16x16x32_bf16 v[106:109], v[160:163], v[216:219], v[106:109]
	v_mfma_f32_16x16x32_bf16 v[94:97], v[152:155], v[224:227], v[94:97]
	v_mfma_f32_16x16x32_bf16 v[90:93], v[160:163], v[224:227], v[90:93]
	v_mfma_f32_16x16x32_bf16 v[78:81], v[152:155], v[232:235], v[78:81]
	v_mfma_f32_16x16x32_bf16 v[74:77], v[160:163], v[232:235], v[74:77]
	s_setprio 0
	s_setprio 1
	v_mfma_f32_16x16x32_bf16 v[118:121], v[166:169], v[202:205], v[118:121]
	v_mfma_f32_16x16x32_bf16 v[114:117], v[174:177], v[202:205], v[114:117]
	v_mfma_f32_16x16x32_bf16 v[102:105], v[166:169], v[212:215], v[102:105]
	v_mfma_f32_16x16x32_bf16 v[98:101], v[174:177], v[212:215], v[98:101]
	v_mfma_f32_16x16x32_bf16 v[86:89], v[166:169], v[220:223], v[86:89]
	v_mfma_f32_16x16x32_bf16 v[82:85], v[174:177], v[220:223], v[82:85]
	v_mfma_f32_16x16x32_bf16 v[70:73], v[166:169], v[228:231], v[70:73]
	v_mfma_f32_16x16x32_bf16 v[66:69], v[174:177], v[228:231], v[66:69]
	v_mfma_f32_16x16x32_bf16 v[118:121], v[170:173], v[208:211], v[118:121]
	v_mfma_f32_16x16x32_bf16 v[114:117], v[178:181], v[208:211], v[114:117]
	v_mfma_f32_16x16x32_bf16 v[102:105], v[170:173], v[216:219], v[102:105]
	v_mfma_f32_16x16x32_bf16 v[98:101], v[178:181], v[216:219], v[98:101]
	v_mfma_f32_16x16x32_bf16 v[86:89], v[170:173], v[224:227], v[86:89]
	v_mfma_f32_16x16x32_bf16 v[82:85], v[178:181], v[224:227], v[82:85]
	v_mfma_f32_16x16x32_bf16 v[70:73], v[170:173], v[232:235], v[70:73]
	v_mfma_f32_16x16x32_bf16 v[66:69], v[178:181], v[232:235], v[66:69]
	s_setprio 0
	s_barrier
; #define PG8_STAGE(bufoff, gbase, voff) do { _Pragma("unroll") for (int _i = 0; _i < 2; ++_i) \
;         __builtin_amdgcn_global_load_lds((const unsigned*)((const char*)(gbase) + (voff)[_i]), (PG8_LAS unsigned*)(lds + (bufoff) + ldsw + _i * 8192), 16, 0, 0); } while (0)
; #define PG8_LDA(dst, b, h) do { _Pragma("unroll") for (int m = 0; m < 4; ++m) _Pragma("unroll") for (int k = 0; k < 2; ++k) dst[m][k] = *(const PG8_LAS bf16x8*)(lds + PG8_SA(b, h) + aoff + m * 2048 + k * 1024); } while (0)
; #define PG8_LDB(dst, b, h) do { _Pragma("unroll") for (int n = 0; n < 2; ++n) _Pragma("unroll") for (int k = 0; k < 2; ++k) dst[n][k] = *(const PG8_LAS bf16x8*)(lds + PG8_SB(b, h) + boff + n * 2048 + k * 1024); } while (0)
; #define PG8_MMA(ai, bj, At, Bt) do { __builtin_amdgcn_s_setprio(1); _Pragma("unroll") for (int m = 0; m < 4; ++m) _Pragma("unroll") for (int n = 0; n < 2; ++n) _Pragma("unroll") for (int k = 0; k < 2; ++k) \
;         acc[ai][bj][m][n] = __builtin_amdgcn_mfma_f32_16x16x32_bf16(Bt[n][k], At[m][k], acc[ai][bj][m][n], 0, 0, 0); __builtin_amdgcn_s_setprio(0); } while (0)
; #define PG8_WAIT_V(n) asm volatile("s_waitcnt vmcnt(" #n ")" ::: "memory")
; #define PG8_WAIT_L(n) asm volatile("s_waitcnt lgkmcnt(" #n ")" ::: "memory")
; #define PG8_BAR __builtin_amdgcn_s_barrier()
; #define PG8_SCHED __builtin_amdgcn_sched_barrier(0)
; template <class Epi, class Sched, bool ALIGN_EPI = false, bool SP2 = false>
; __device__ __forceinline__ void gemm_phase(PG8_LAS unsigned char* lds, const Gemm g, const Sched& S, const Epi& E) {
;     ...
;             PG8_LDB(B0, 0, 0); PG8_LDB(B1, 0, 1); PG8_SCHED; PG8_LDA(At, 0, 0); PG8_STAGE(PG8_SA(1, 1), a1 + hstep, voffA);
;     ...
;             PG8_LDA(At, 1, 1); PG8_STAGE(PG8_SB(1, 0), b3, voffB); PG8_STAGE(PG8_SB(1, 1), b3 + hstep, voffB); PG8_STAGE(PG8_SA(1, 0), a3, voffA);
;             PG8_WAIT_V(8); PG8_WAIT_L(0); PG8_BAR; PG8_MMA(1, 0, At, B0); PG8_MMA(1, 1, At, B1); PG8_BAR; PG8_SCHED;
	s_add_i32 s59, s59, s93
	v_lshl_add_u64 v[136:137], v[136:137], 0, s[66:67]
	s_mov_b32 m0, s59
	ds_read_b128 v[202:205], v165 offset:49152
	ds_read_b128 v[208:211], v165 offset:50176
	ds_read_b128 v[212:215], v165 offset:51200
	ds_read_b128 v[216:219], v165 offset:52224
	ds_read_b128 v[220:223], v165 offset:53248
	ds_read_b128 v[224:227], v165 offset:54272
	ds_read_b128 v[228:231], v165 offset:55296
	ds_read_b128 v[232:235], v165 offset:56320
	global_load_lds_dwordx4 v[136:137], off
	v_lshl_add_u64 v[136:137], v[144:145], 0, s[66:67]
	s_add_i32 m0, s59, 0x2000
	s_add_i32 s59, s83, s93
	global_load_lds_dwordx4 v[136:137], off
	v_lshl_add_u64 v[136:137], v[182:183], 0, s[66:67]
	s_mov_b32 m0, s59
	s_nop 0
	global_load_lds_dwordx4 v[136:137], off
	v_lshl_add_u64 v[136:137], v[236:237], 0, s[66:67]
	s_add_i32 m0, s59, 0x2000
	s_nop 0
	global_load_lds_dwordx4 v[136:137], off
	v_lshl_add_u64 v[136:137], v[238:239], 0, s[66:67]
	s_mov_b32 m0, s73
	s_nop 0
	global_load_lds_dwordx4 v[136:137], off
	v_lshl_add_u64 v[136:137], v[240:241], 0, s[66:67]
	s_mov_b32 m0, s50
	s_nop 0
	global_load_lds_dwordx4 v[136:137], off
	s_waitcnt vmcnt(8)
	s_waitcnt lgkmcnt(0)
	s_barrier
	s_setprio 1
	s_waitcnt lgkmcnt(0)
	v_mfma_f32_16x16x32_bf16 v[62:65], v[148:151], v[202:205], v[62:65]
	v_mfma_f32_16x16x32_bf16 v[58:61], v[156:159], v[202:205], v[58:61]
	v_mfma_f32_16x16x32_bf16 v[46:49], v[148:151], v[212:215], v[46:49]
	v_mfma_f32_16x16x32_bf16 v[42:45], v[156:159], v[212:215], v[42:45]
	v_mfma_f32_16x16x32_bf16 v[30:33], v[148:151], v[220:223], v[30:33]
	v_mfma_f32_16x16x32_bf16 v[26:29], v[156:159], v[220:223], v[26:29]
	v_mfma_f32_16x16x32_bf16 v[14:17], v[148:151], v[228:231], v[14:17]
	v_mfma_f32_16x16x32_bf16 v[10:13], v[156:159], v[228:231], v[10:13]
	v_mfma_f32_16x16x32_bf16 v[62:65], v[152:155], v[208:211], v[62:65]
	v_mfma_f32_16x16x32_bf16 v[58:61], v[160:163], v[208:211], v[58:61]
	v_mfma_f32_16x16x32_bf16 v[46:49], v[152:155], v[216:219], v[46:49]
	v_mfma_f32_16x16x32_bf16 v[42:45], v[160:163], v[216:219], v[42:45]
	v_mfma_f32_16x16x32_bf16 v[30:33], v[152:155], v[224:227], v[30:33]
	v_mfma_f32_16x16x32_bf16 v[26:29], v[160:163], v[224:227], v[26:29]
	v_mfma_f32_16x16x32_bf16 v[14:17], v[152:155], v[232:235], v[14:17]
	v_mfma_f32_16x16x32_bf16 v[10:13], v[160:163], v[232:235], v[10:13]
	s_setprio 0
	s_setprio 1
	v_mfma_f32_16x16x32_bf16 v[54:57], v[166:169], v[202:205], v[54:57]
	v_mfma_f32_16x16x32_bf16 v[50:53], v[174:177], v[202:205], v[50:53]
	v_mfma_f32_16x16x32_bf16 v[38:41], v[166:169], v[212:215], v[38:41]
	v_mfma_f32_16x16x32_bf16 v[34:37], v[174:177], v[212:215], v[34:37]
	v_mfma_f32_16x16x32_bf16 v[22:25], v[166:169], v[220:223], v[22:25]
	v_mfma_f32_16x16x32_bf16 v[18:21], v[174:177], v[220:223], v[18:21]
	v_mfma_f32_16x16x32_bf16 v[6:9], v[166:169], v[228:231], v[6:9]
	v_mfma_f32_16x16x32_bf16 v[2:5], v[174:177], v[228:231], v[2:5]
	v_mfma_f32_16x16x32_bf16 v[54:57], v[170:173], v[208:211], v[54:57]
	v_mfma_f32_16x16x32_bf16 v[50:53], v[178:181], v[208:211], v[50:53]
	v_mfma_f32_16x16x32_bf16 v[38:41], v[170:173], v[216:219], v[38:41]
	v_mfma_f32_16x16x32_bf16 v[34:37], v[178:181], v[216:219], v[34:37]
	v_mfma_f32_16x16x32_bf16 v[22:25], v[170:173], v[224:227], v[22:25]
	v_mfma_f32_16x16x32_bf16 v[18:21], v[178:181], v[224:227], v[18:21]
	v_mfma_f32_16x16x32_bf16 v[6:9], v[170:173], v[232:235], v[6:9]
	v_mfma_f32_16x16x32_bf16 v[2:5], v[178:181], v[232:235], v[2:5]
	s_setprio 0
	s_barrier
	s_add_u32 s48, s48, 0x100
	s_addc_u32 s49, s49, 0
	s_add_u32 s80, s80, 0x100
	s_addc_u32 s81, s81, 0
	s_cmp_ge_u32 s82, s79
	s_mov_b32 s76, s82
	s_cbranch_scc0 .LBB0_849
	s_branch .Lkq_exit
	s_nop 0
	s_nop 0
	s_nop 0
	s_nop 0
	s_nop 0
	s_nop 0
	s_nop 0
.LBB0_849:
	s_add_i32 s82, s76, 2
	s_add_u32 s83, s48, 0x80
	s_addc_u32 s77, s49, 0
	s_add_i32 s59, 0, 0x10000
	s_cmp_eq_u32 s72, s76
	s_cselect_b32 s77, s9, s77
	s_cselect_b32 s76, s8, s83
	v_add_u32_e32 v136, s59, v147
	s_cselect_b32 vcc_hi, s47, s81
	s_cselect_b32 vcc_lo, s46, s80
	s_add_i32 s83, 0, 0x14000
	ds_read_b128 v[148:151], v136
	ds_read_b128 v[152:155], v136 offset:1024
	ds_read_b128 v[156:159], v136 offset:2048
	ds_read_b128 v[160:163], v136 offset:3072
	v_add_u32_e32 v136, s83, v147
	ds_read_b128 v[166:169], v136
	ds_read_b128 v[170:173], v136 offset:1024
	ds_read_b128 v[174:177], v136 offset:2048
	ds_read_b128 v[178:181], v136 offset:3072
	v_lshl_add_u64 v[136:137], s[48:49], 0, v[132:133]
	s_add_i32 m0, s94, 0xc000
	ds_read_b128 v[202:205], v165
	ds_read_b128 v[208:211], v165 offset:1024
	ds_read_b128 v[212:215], v165 offset:2048
	ds_read_b128 v[216:219], v165 offset:3072
	ds_read_b128 v[220:223], v165 offset:4096
	ds_read_b128 v[224:227], v165 offset:5120
	ds_read_b128 v[228:231], v165 offset:6144
	ds_read_b128 v[232:235], v165 offset:7168
	global_load_lds_dwordx4 v[136:137], off
	v_lshl_add_u64 v[136:137], s[48:49], 0, v[134:135]
	s_add_i32 m0, s94, 0xe000
	s_nop 0
	global_load_lds_dwordx4 v[136:137], off
	s_waitcnt vmcnt(8)
	s_waitcnt lgkmcnt(0)
	s_barrier
; #define PG8_STAGE(bufoff, gbase, voff) do { _Pragma("unroll") for (int _i = 0; _i < 2; ++_i) \
;         __builtin_amdgcn_global_load_lds((const unsigned*)((const char*)(gbase) + (voff)[_i]), (PG8_LAS unsigned*)(lds + (bufoff) + ldsw + _i * 8192), 16, 0, 0); } while (0)
; #define PG8_LDA(dst, b, h) do { _Pragma("unroll") for (int m = 0; m < 4; ++m) _Pragma("unroll") for (int k = 0; k < 2; ++k) dst[m][k] = *(const PG8_LAS bf16x8*)(lds + PG8_SA(b, h) + aoff + m * 2048 + k * 1024); } while (0)
; #define PG8_LDB(dst, b, h) do { _Pragma("unroll") for (int n = 0; n < 2; ++n) _Pragma("unroll") for (int k = 0; k < 2; ++k) dst[n][k] = *(const PG8_LAS bf16x8*)(lds + PG8_SB(b, h) + boff + n * 2048 + k * 1024); } while (0)
; #define PG8_MMA(ai, bj, At, Bt) do { __builtin_amdgcn_s_setprio(1); _Pragma("unroll") for (int m = 0; m < 4; ++m) _Pragma("unroll") for (int n = 0; n < 2; ++n) _Pragma("unroll") for (int k = 0; k < 2; ++k) \
;         acc[ai][bj][m][n] = __builtin_amdgcn_mfma_f32_16x16x32_bf16(Bt[n][k], At[m][k], acc[ai][bj][m][n], 0, 0, 0); __builtin_amdgcn_s_setprio(0); } while (0)
; #define PG8_WAIT_V(n) asm volatile("s_waitcnt vmcnt(" #n ")" ::: "memory")
; template <class Epi, class Sched, bool ALIGN_EPI = false, bool SP2 = false>
; __device__ __forceinline__ void gemm_phase(PG8_LAS unsigned char* lds, const Gemm g, const Sched& S, const Epi& E) {
;     ...
;             PG8_LDB(B0, 0, 0); PG8_LDB(B1, 0, 1); PG8_SCHED; PG8_LDA(At, 0, 0); PG8_STAGE(PG8_SA(1, 1), a1 + hstep, voffA);
;             PG8_WAIT_V(8); PG8_WAIT_L(0); PG8_BAR; PG8_MMA(0, 0, At, B0); PG8_MMA(0, 1, At, B1); PG8_BAR; PG8_SCHED;
;             PG8_LDA(At, 0, 1); PG8_STAGE(PG8_SB(0, 0), b2, voffB); PG8_STAGE(PG8_SB(0, 1), b2 + hstep, voffB); PG8_STAGE(PG8_SA(0, 0), a2, voffA);
;             PG8_WAIT_V(8); PG8_WAIT_L(0); PG8_BAR; PG8_MMA(1, 0, At, B0); PG8_MMA(1, 1, At, B1); PG8_BAR; PG8_SCHED;
;             PG8_LDB(B0, 1, 0); PG8_LDB(B1, 1, 1); PG8_SCHED; PG8_LDA(At, 1, 0); PG8_STAGE(PG8_SA(0, 1), a2 + hstep, voffA);
;             PG8_WAIT_V(8); PG8_WAIT_L(0); PG8_BAR; PG8_MMA(0, 0, At, B0); PG8_MMA(0, 1, At, B1); PG8_BAR; PG8_SCHED;
;             PG8_LDA(At, 1, 1); PG8_STAGE(PG8_SB(1, 0), b3, voffB); PG8_STAGE(PG8_SB(1, 1), b3 + hstep, voffB); PG8_STAGE(PG8_SA(1, 0), a3, voffA);
;             PG8_WAIT_V(8); PG8_WAIT_L(0); PG8_BAR; PG8_MMA(1, 0, At, B0); PG8_MMA(1, 1, At, B1); PG8_BAR; PG8_SCHED;
	s_setprio 1
	s_waitcnt lgkmcnt(0)
	v_mfma_f32_16x16x32_bf16 v[126:129], v[148:151], v[202:205], v[126:129]
	v_mfma_f32_16x16x32_bf16 v[122:125], v[156:159], v[202:205], v[122:125]
	v_mfma_f32_16x16x32_bf16 v[110:113], v[148:151], v[212:215], v[110:113]
	v_mfma_f32_16x16x32_bf16 v[106:109], v[156:159], v[212:215], v[106:109]
	v_mfma_f32_16x16x32_bf16 v[94:97], v[148:151], v[220:223], v[94:97]
	v_mfma_f32_16x16x32_bf16 v[90:93], v[156:159], v[220:223], v[90:93]
	v_mfma_f32_16x16x32_bf16 v[78:81], v[148:151], v[228:231], v[78:81]
	v_mfma_f32_16x16x32_bf16 v[74:77], v[156:159], v[228:231], v[74:77]
	v_mfma_f32_16x16x32_bf16 v[126:129], v[152:155], v[208:211], v[126:129]
	v_mfma_f32_16x16x32_bf16 v[122:125], v[160:163], v[208:211], v[122:125]
	v_mfma_f32_16x16x32_bf16 v[110:113], v[152:155], v[216:219], v[110:113]
	v_mfma_f32_16x16x32_bf16 v[106:109], v[160:163], v[216:219], v[106:109]
	v_mfma_f32_16x16x32_bf16 v[94:97], v[152:155], v[224:227], v[94:97]
	v_mfma_f32_16x16x32_bf16 v[90:93], v[160:163], v[224:227], v[90:93]
	v_mfma_f32_16x16x32_bf16 v[78:81], v[152:155], v[232:235], v[78:81]
	v_mfma_f32_16x16x32_bf16 v[74:77], v[160:163], v[232:235], v[74:77]
	s_setprio 0
	s_setprio 1
	v_mfma_f32_16x16x32_bf16 v[118:121], v[166:169], v[202:205], v[118:121]
	v_mfma_f32_16x16x32_bf16 v[114:117], v[174:177], v[202:205], v[114:117]
	v_mfma_f32_16x16x32_bf16 v[102:105], v[166:169], v[212:215], v[102:105]
	v_mfma_f32_16x16x32_bf16 v[98:101], v[174:177], v[212:215], v[98:101]
	v_mfma_f32_16x16x32_bf16 v[86:89], v[166:169], v[220:223], v[86:89]
	v_mfma_f32_16x16x32_bf16 v[82:85], v[174:177], v[220:223], v[82:85]
	v_mfma_f32_16x16x32_bf16 v[70:73], v[166:169], v[228:231], v[70:73]
	v_mfma_f32_16x16x32_bf16 v[66:69], v[174:177], v[228:231], v[66:69]
	v_mfma_f32_16x16x32_bf16 v[118:121], v[170:173], v[208:211], v[118:121]
	v_mfma_f32_16x16x32_bf16 v[114:117], v[178:181], v[208:211], v[114:117]
	v_mfma_f32_16x16x32_bf16 v[102:105], v[170:173], v[216:219], v[102:105]
	v_mfma_f32_16x16x32_bf16 v[98:101], v[178:181], v[216:219], v[98:101]
	v_mfma_f32_16x16x32_bf16 v[86:89], v[170:173], v[224:227], v[86:89]
	v_mfma_f32_16x16x32_bf16 v[82:85], v[178:181], v[224:227], v[82:85]
	v_mfma_f32_16x16x32_bf16 v[70:73], v[170:173], v[232:235], v[70:73]
	v_mfma_f32_16x16x32_bf16 v[66:69], v[178:181], v[232:235], v[66:69]
	s_setprio 0
	s_barrier
	s_add_i32 s59, s59, s93
	v_lshl_add_u64 v[136:137], vcc, 0, v[0:1]
	s_mov_b32 m0, s59
	ds_read_b128 v[202:205], v165 offset:16384
	ds_read_b128 v[208:211], v165 offset:17408
	ds_read_b128 v[212:215], v165 offset:18432
	ds_read_b128 v[216:219], v165 offset:19456
	ds_read_b128 v[220:223], v165 offset:20480
	ds_read_b128 v[224:227], v165 offset:21504
	ds_read_b128 v[228:231], v165 offset:22528
	ds_read_b128 v[232:235], v165 offset:23552
	global_load_lds_dwordx4 v[136:137], off
	s_add_i32 m0, s59, 0x2000
	v_lshl_add_u64 v[144:145], vcc, 0, v[130:131]
	s_add_u32 vcc_lo, vcc_lo, s10
	s_addc_u32 vcc_hi, vcc_hi, 0
	s_add_i32 s59, s83, s93
	global_load_lds_dwordx4 v[144:145], off
	v_lshl_add_u64 v[182:183], vcc, 0, v[0:1]
	s_mov_b32 m0, s59
	v_lshl_add_u64 v[236:237], vcc, 0, v[130:131]
	global_load_lds_dwordx4 v[182:183], off
	s_add_i32 m0, s59, 0x2000
	v_lshl_add_u64 v[238:239], s[76:77], 0, v[0:1]
	global_load_lds_dwordx4 v[236:237], off
	s_mov_b32 m0, s94
	v_lshl_add_u64 v[240:241], s[76:77], 0, v[130:131]
	global_load_lds_dwordx4 v[238:239], off
	s_mov_b32 m0, s95
	s_nop 0
	global_load_lds_dwordx4 v[240:241], off
	s_waitcnt vmcnt(8)
	s_waitcnt lgkmcnt(0)
	s_barrier
	s_setprio 1
	s_waitcnt lgkmcnt(0)
	v_mfma_f32_16x16x32_bf16 v[62:65], v[148:151], v[202:205], v[62:65]
	v_mfma_f32_16x16x32_bf16 v[58:61], v[156:159], v[202:205], v[58:61]
	v_mfma_f32_16x16x32_bf16 v[46:49], v[148:151], v[212:215], v[46:49]
	v_mfma_f32_16x16x32_bf16 v[42:45], v[156:159], v[212:215], v[42:45]
	v_mfma_f32_16x16x32_bf16 v[30:33], v[148:151], v[220:223], v[30:33]
	v_mfma_f32_16x16x32_bf16 v[26:29], v[156:159], v[220:223], v[26:29]
	v_mfma_f32_16x16x32_bf16 v[14:17], v[148:151], v[228:231], v[14:17]
	v_mfma_f32_16x16x32_bf16 v[10:13], v[156:159], v[228:231], v[10:13]
	v_mfma_f32_16x16x32_bf16 v[62:65], v[152:155], v[208:211], v[62:65]
	v_mfma_f32_16x16x32_bf16 v[58:61], v[160:163], v[208:211], v[58:61]
	v_mfma_f32_16x16x32_bf16 v[46:49], v[152:155], v[216:219], v[46:49]
	v_mfma_f32_16x16x32_bf16 v[42:45], v[160:163], v[216:219], v[42:45]
	v_mfma_f32_16x16x32_bf16 v[30:33], v[152:155], v[224:227], v[30:33]
	v_mfma_f32_16x16x32_bf16 v[26:29], v[160:163], v[224:227], v[26:29]
	v_mfma_f32_16x16x32_bf16 v[14:17], v[152:155], v[232:235], v[14:17]
	v_mfma_f32_16x16x32_bf16 v[10:13], v[160:163], v[232:235], v[10:13]
	s_setprio 0
	s_setprio 1
	v_mfma_f32_16x16x32_bf16 v[54:57], v[166:169], v[202:205], v[54:57]
	v_mfma_f32_16x16x32_bf16 v[50:53], v[174:177], v[202:205], v[50:53]
	v_mfma_f32_16x16x32_bf16 v[38:41], v[166:169], v[212:215], v[38:41]
	v_mfma_f32_16x16x32_bf16 v[34:37], v[174:177], v[212:215], v[34:37]
	v_mfma_f32_16x16x32_bf16 v[22:25], v[166:169], v[220:223], v[22:25]
	v_mfma_f32_16x16x32_bf16 v[18:21], v[174:177], v[220:223], v[18:21]
	v_mfma_f32_16x16x32_bf16 v[6:9], v[166:169], v[228:231], v[6:9]
	v_mfma_f32_16x16x32_bf16 v[2:5], v[174:177], v[228:231], v[2:5]
	v_mfma_f32_16x16x32_bf16 v[54:57], v[170:173], v[208:211], v[54:57]
	v_mfma_f32_16x16x32_bf16 v[50:53], v[178:181], v[208:211], v[50:53]
	v_mfma_f32_16x16x32_bf16 v[38:41], v[170:173], v[216:219], v[38:41]
	v_mfma_f32_16x16x32_bf16 v[34:37], v[178:181], v[216:219], v[34:37]
	v_mfma_f32_16x16x32_bf16 v[22:25], v[170:173], v[224:227], v[22:25]
	v_mfma_f32_16x16x32_bf16 v[18:21], v[178:181], v[224:227], v[18:21]
	v_mfma_f32_16x16x32_bf16 v[6:9], v[170:173], v[232:235], v[6:9]
	v_mfma_f32_16x16x32_bf16 v[2:5], v[178:181], v[232:235], v[2:5]
	s_setprio 0
	s_barrier
; #define PG8_STAGE(bufoff, gbase, voff) do { _Pragma("unroll") for (int _i = 0; _i < 2; ++_i) \
;         __builtin_amdgcn_global_load_lds((const unsigned*)((const char*)(gbase) + (voff)[_i]), (PG8_LAS unsigned*)(lds + (bufoff) + ldsw + _i * 8192), 16, 0, 0); } while (0)
; #define PG8_LDA(dst, b, h) do { _Pragma("unroll") for (int m = 0; m < 4; ++m) _Pragma("unroll") for (int k = 0; k < 2; ++k) dst[m][k] = *(const PG8_LAS bf16x8*)(lds + PG8_SA(b, h) + aoff + m * 2048 + k * 1024); } while (0)
; #define PG8_LDB(dst, b, h) do { _Pragma("unroll") for (int n = 0; n < 2; ++n) _Pragma("unroll") for (int k = 0; k < 2; ++k) dst[n][k] = *(const PG8_LAS bf16x8*)(lds + PG8_SB(b, h) + boff + n * 2048 + k * 1024); } while (0)
; #define PG8_MMA(ai, bj, At, Bt) do { __builtin_amdgcn_s_setprio(1); _Pragma("unroll") for (int m = 0; m < 4; ++m) _Pragma("unroll") for (int n = 0; n < 2; ++n) _Pragma("unroll") for (int k = 0; k < 2; ++k) \
;         acc[ai][bj][m][n] = __builtin_amdgcn_mfma_f32_16x16x32_bf16(Bt[n][k], At[m][k], acc[ai][bj][m][n], 0, 0, 0); __builtin_amdgcn_s_setprio(0); } while (0)
; #define PG8_WAIT_V(n) asm volatile("s_waitcnt vmcnt(" #n ")" ::: "memory")
; #define PG8_WAIT_L(n) asm volatile("s_waitcnt lgkmcnt(" #n ")" ::: "memory")
; #define PG8_BAR __builtin_amdgcn_s_barrier()
; #define PG8_SCHED __builtin_amdgcn_sched_barrier(0)
; template <class Epi, class Sched, bool ALIGN_EPI = false, bool SP2 = false>
; __device__ __forceinline__ void gemm_phase(PG8_LAS unsigned char* lds, const Gemm g, const Sched& S, const Epi& E) {
;     ...
;             PG8_LDB(B0, 1, 0); PG8_LDB(B1, 1, 1); PG8_SCHED; PG8_LDA(At, 1, 0); PG8_STAGE(PG8_SA(0, 1), a2 + hstep, voffA);
;             PG8_WAIT_V(8); PG8_WAIT_L(0); PG8_BAR; PG8_MMA(0, 0, At, B0); PG8_MMA(0, 1, At, B1); PG8_BAR; PG8_SCHED;
;             PG8_LDA(At, 1, 1); PG8_STAGE(PG8_SB(1, 0), b3, voffB); PG8_STAGE(PG8_SB(1, 1), b3 + hstep, voffB); PG8_STAGE(PG8_SA(1, 0), a3, voffA);
;             PG8_WAIT_V(8); PG8_WAIT_L(0); PG8_BAR; PG8_MMA(1, 0, At, B0); PG8_MMA(1, 1, At, B1); PG8_BAR; PG8_SCHED;
	s_add_i32 s59, 0, 0x18000
	s_add_i32 s83, 0, 0x1c000
	v_add_u32_e32 v160, s59, v147
	v_add_u32_e32 v178, s83, v147
	ds_read_b128 v[148:151], v160
	ds_read_b128 v[152:155], v160 offset:1024
	ds_read_b128 v[156:159], v160 offset:2048
	ds_read_b128 v[160:163], v160 offset:3072
	ds_read_b128 v[166:169], v178
	ds_read_b128 v[170:173], v178 offset:1024
	ds_read_b128 v[174:177], v178 offset:2048
	ds_read_b128 v[178:181], v178 offset:3072
	s_add_u32 s76, s76, s10
	s_addc_u32 s77, s77, 0
	s_mov_b32 m0, s84
	v_lshl_add_u64 v[242:243], s[76:77], 0, v[0:1]
	ds_read_b128 v[202:205], v165 offset:32768
	ds_read_b128 v[208:211], v165 offset:33792
	ds_read_b128 v[212:215], v165 offset:34816
	ds_read_b128 v[216:219], v165 offset:35840
	ds_read_b128 v[220:223], v165 offset:36864
	ds_read_b128 v[224:227], v165 offset:37888
	ds_read_b128 v[228:231], v165 offset:38912
	ds_read_b128 v[232:235], v165 offset:39936
	global_load_lds_dwordx4 v[242:243], off
	v_lshl_add_u64 v[242:243], s[76:77], 0, v[130:131]
	s_mov_b32 m0, s74
	s_nop 0
	global_load_lds_dwordx4 v[242:243], off
	s_waitcnt vmcnt(8)
	s_waitcnt lgkmcnt(0)
	s_barrier
	s_setprio 1
	s_waitcnt lgkmcnt(0)
	v_mfma_f32_16x16x32_bf16 v[126:129], v[148:151], v[202:205], v[126:129]
	v_mfma_f32_16x16x32_bf16 v[122:125], v[156:159], v[202:205], v[122:125]
	v_mfma_f32_16x16x32_bf16 v[110:113], v[148:151], v[212:215], v[110:113]
	v_mfma_f32_16x16x32_bf16 v[106:109], v[156:159], v[212:215], v[106:109]
	v_mfma_f32_16x16x32_bf16 v[94:97], v[148:151], v[220:223], v[94:97]
	v_mfma_f32_16x16x32_bf16 v[90:93], v[156:159], v[220:223], v[90:93]
	v_mfma_f32_16x16x32_bf16 v[78:81], v[148:151], v[228:231], v[78:81]
	v_mfma_f32_16x16x32_bf16 v[74:77], v[156:159], v[228:231], v[74:77]
	v_mfma_f32_16x16x32_bf16 v[126:129], v[152:155], v[208:211], v[126:129]
	v_mfma_f32_16x16x32_bf16 v[122:125], v[160:163], v[208:211], v[122:125]
	v_mfma_f32_16x16x32_bf16 v[110:113], v[152:155], v[216:219], v[110:113]
	v_mfma_f32_16x16x32_bf16 v[106:109], v[160:163], v[216:219], v[106:109]
	v_mfma_f32_16x16x32_bf16 v[94:97], v[152:155], v[224:227], v[94:97]
	v_mfma_f32_16x16x32_bf16 v[90:93], v[160:163], v[224:227], v[90:93]
	v_mfma_f32_16x16x32_bf16 v[78:81], v[152:155], v[232:235], v[78:81]
	v_mfma_f32_16x16x32_bf16 v[74:77], v[160:163], v[232:235], v[74:77]
	s_setprio 0
	s_setprio 1
	v_mfma_f32_16x16x32_bf16 v[118:121], v[166:169], v[202:205], v[118:121]
	v_mfma_f32_16x16x32_bf16 v[114:117], v[174:177], v[202:205], v[114:117]
	v_mfma_f32_16x16x32_bf16 v[102:105], v[166:169], v[212:215], v[102:105]
	v_mfma_f32_16x16x32_bf16 v[98:101], v[174:177], v[212:215], v[98:101]
	v_mfma_f32_16x16x32_bf16 v[86:89], v[166:169], v[220:223], v[86:89]
	v_mfma_f32_16x16x32_bf16 v[82:85], v[174:177], v[220:223], v[82:85]
	v_mfma_f32_16x16x32_bf16 v[70:73], v[166:169], v[228:231], v[70:73]
	v_mfma_f32_16x16x32_bf16 v[66:69], v[174:177], v[228:231], v[66:69]
	v_mfma_f32_16x16x32_bf16 v[118:121], v[170:173], v[208:211], v[118:121]
	v_mfma_f32_16x16x32_bf16 v[114:117], v[178:181], v[208:211], v[114:117]
	v_mfma_f32_16x16x32_bf16 v[102:105], v[170:173], v[216:219], v[102:105]
	v_mfma_f32_16x16x32_bf16 v[98:101], v[178:181], v[216:219], v[98:101]
	v_mfma_f32_16x16x32_bf16 v[86:89], v[170:173], v[224:227], v[86:89]
	v_mfma_f32_16x16x32_bf16 v[82:85], v[178:181], v[224:227], v[82:85]
	v_mfma_f32_16x16x32_bf16 v[70:73], v[170:173], v[232:235], v[70:73]
	v_mfma_f32_16x16x32_bf16 v[66:69], v[178:181], v[232:235], v[66:69]
	s_setprio 0
	s_barrier
	s_add_i32 s59, s59, s93
	v_lshl_add_u64 v[136:137], v[136:137], 0, s[66:67]
	s_mov_b32 m0, s59
	ds_read_b128 v[202:205], v165 offset:49152
	ds_read_b128 v[208:211], v165 offset:50176
	ds_read_b128 v[212:215], v165 offset:51200
	ds_read_b128 v[216:219], v165 offset:52224
	ds_read_b128 v[220:223], v165 offset:53248
	ds_read_b128 v[224:227], v165 offset:54272
	ds_read_b128 v[228:231], v165 offset:55296
	ds_read_b128 v[232:235], v165 offset:56320
	global_load_lds_dwordx4 v[136:137], off
	v_lshl_add_u64 v[136:137], v[144:145], 0, s[66:67]
	s_add_i32 m0, s59, 0x2000
	s_add_i32 s59, s83, s93
	global_load_lds_dwordx4 v[136:137], off
	v_lshl_add_u64 v[136:137], v[182:183], 0, s[66:67]
	s_mov_b32 m0, s59
	s_nop 0
	global_load_lds_dwordx4 v[136:137], off
	v_lshl_add_u64 v[136:137], v[236:237], 0, s[66:67]
	s_add_i32 m0, s59, 0x2000
	s_nop 0
	global_load_lds_dwordx4 v[136:137], off
	v_lshl_add_u64 v[136:137], v[238:239], 0, s[66:67]
	s_mov_b32 m0, s73
	s_nop 0
	global_load_lds_dwordx4 v[136:137], off
	v_lshl_add_u64 v[136:137], v[240:241], 0, s[66:67]
	s_mov_b32 m0, s50
	s_nop 0
	global_load_lds_dwordx4 v[136:137], off
	s_waitcnt vmcnt(8)
	s_waitcnt lgkmcnt(0)
	s_barrier
; #define PG8_STAGE(bufoff, gbase, voff) do { _Pragma("unroll") for (int _i = 0; _i < 2; ++_i) \
;         __builtin_amdgcn_global_load_lds((const unsigned*)((const char*)(gbase) + (voff)[_i]), (PG8_LAS unsigned*)(lds + (bufoff) + ldsw + _i * 8192), 16, 0, 0); } while (0)
; #define PG8_LDA(dst, b, h) do { _Pragma("unroll") for (int m = 0; m < 4; ++m) _Pragma("unroll") for (int k = 0; k < 2; ++k) dst[m][k] = *(const PG8_LAS bf16x8*)(lds + PG8_SA(b, h) + aoff + m * 2048 + k * 1024); } while (0)
; #define PG8_MMA(ai, bj, At, Bt) do { __builtin_amdgcn_s_setprio(1); _Pragma("unroll") for (int m = 0; m < 4; ++m) _Pragma("unroll") for (int n = 0; n < 2; ++n) _Pragma("unroll") for (int k = 0; k < 2; ++k) \
;         acc[ai][bj][m][n] = __builtin_amdgcn_mfma_f32_16x16x32_bf16(Bt[n][k], At[m][k], acc[ai][bj][m][n], 0, 0, 0); __builtin_amdgcn_s_setprio(0); } while (0)
; #define PG8_WAIT_V(n) asm volatile("s_waitcnt vmcnt(" #n ")" ::: "memory")
; #define PG8_WAIT_L(n) asm volatile("s_waitcnt lgkmcnt(" #n ")" ::: "memory")
; #define PG8_BAR __builtin_amdgcn_s_barrier()
; #define PG8_SCHED __builtin_amdgcn_sched_barrier(0)
; template <class Epi, class Sched, bool ALIGN_EPI = false, bool SP2 = false>
; __device__ __forceinline__ void gemm_phase(PG8_LAS unsigned char* lds, const Gemm g, const Sched& S, const Epi& E) {
;     ...
; #pragma unroll
;     for (int a = 0; a < 2; ++a)
; #pragma unroll
;         for (int b = 0; b < 2; ++b)
; #pragma unroll
;             for (int m = 0; m < 4; ++m)
; #pragma unroll
;                 for (int n = 0; n < 2; ++n) acc[a][b][m][n] = (f32x4){0.f, 0.f, 0.f, 0.f};
;     ...
;             PG8_WAIT_V(8); PG8_WAIT_L(0); PG8_BAR; PG8_MMA(0, 0, At, B0); PG8_MMA(0, 1, At, B1); PG8_BAR; PG8_SCHED;
;             PG8_LDA(At, 1, 1); PG8_STAGE(PG8_SB(1, 0), b3, voffB); PG8_STAGE(PG8_SB(1, 1), b3 + hstep, voffB); PG8_STAGE(PG8_SA(1, 0), a3, voffA);
;             PG8_WAIT_V(8); PG8_WAIT_L(0); PG8_BAR; PG8_MMA(1, 0, At, B0); PG8_MMA(1, 1, At, B1); PG8_BAR; PG8_SCHED;
	s_setprio 1
	s_waitcnt lgkmcnt(0)
	v_mfma_f32_16x16x32_bf16 v[62:65], v[148:151], v[202:205], v[62:65]
	v_mfma_f32_16x16x32_bf16 v[58:61], v[156:159], v[202:205], v[58:61]
	v_mfma_f32_16x16x32_bf16 v[46:49], v[148:151], v[212:215], v[46:49]
	v_mfma_f32_16x16x32_bf16 v[42:45], v[156:159], v[212:215], v[42:45]
	v_mfma_f32_16x16x32_bf16 v[30:33], v[148:151], v[220:223], v[30:33]
	v_mfma_f32_16x16x32_bf16 v[26:29], v[156:159], v[220:223], v[26:29]
	v_mfma_f32_16x16x32_bf16 v[14:17], v[148:151], v[228:231], v[14:17]
	v_mfma_f32_16x16x32_bf16 v[10:13], v[156:159], v[228:231], v[10:13]
	v_mfma_f32_16x16x32_bf16 v[62:65], v[152:155], v[208:211], v[62:65]
	v_mfma_f32_16x16x32_bf16 v[58:61], v[160:163], v[208:211], v[58:61]
	v_mfma_f32_16x16x32_bf16 v[46:49], v[152:155], v[216:219], v[46:49]
	v_mfma_f32_16x16x32_bf16 v[42:45], v[160:163], v[216:219], v[42:45]
	v_mfma_f32_16x16x32_bf16 v[30:33], v[152:155], v[224:227], v[30:33]
	v_mfma_f32_16x16x32_bf16 v[26:29], v[160:163], v[224:227], v[26:29]
	v_mfma_f32_16x16x32_bf16 v[14:17], v[152:155], v[232:235], v[14:17]
	v_mfma_f32_16x16x32_bf16 v[10:13], v[160:163], v[232:235], v[10:13]
	s_setprio 0
	s_setprio 1
	v_mfma_f32_16x16x32_bf16 v[54:57], v[166:169], v[202:205], v[54:57]
	v_mfma_f32_16x16x32_bf16 v[50:53], v[174:177], v[202:205], v[50:53]
	v_mfma_f32_16x16x32_bf16 v[38:41], v[166:169], v[212:215], v[38:41]
	v_mfma_f32_16x16x32_bf16 v[34:37], v[174:177], v[212:215], v[34:37]
	v_mfma_f32_16x16x32_bf16 v[22:25], v[166:169], v[220:223], v[22:25]
	v_mfma_f32_16x16x32_bf16 v[18:21], v[174:177], v[220:223], v[18:21]
	v_mfma_f32_16x16x32_bf16 v[6:9], v[166:169], v[228:231], v[6:9]
	v_mfma_f32_16x16x32_bf16 v[2:5], v[174:177], v[228:231], v[2:5]
	v_mfma_f32_16x16x32_bf16 v[54:57], v[170:173], v[208:211], v[54:57]
	v_mfma_f32_16x16x32_bf16 v[50:53], v[178:181], v[208:211], v[50:53]
	v_mfma_f32_16x16x32_bf16 v[38:41], v[170:173], v[216:219], v[38:41]
	v_mfma_f32_16x16x32_bf16 v[34:37], v[178:181], v[216:219], v[34:37]
	v_mfma_f32_16x16x32_bf16 v[22:25], v[170:173], v[224:227], v[22:25]
	v_mfma_f32_16x16x32_bf16 v[18:21], v[178:181], v[224:227], v[18:21]
	v_mfma_f32_16x16x32_bf16 v[6:9], v[170:173], v[232:235], v[6:9]
	v_mfma_f32_16x16x32_bf16 v[2:5], v[178:181], v[232:235], v[2:5]
	s_setprio 0
	s_barrier
	s_add_u32 s48, s48, 0x100
	s_addc_u32 s49, s49, 0
	s_add_u32 s80, s80, 0x100
	s_addc_u32 s81, s81, 0
	s_cmp_ge_u32 s82, s79
	s_mov_b32 s76, s82
	s_cbranch_scc0 .LBB0_849
	s_branch .Lkq_exit
	s_nop 0
	s_nop 0
	s_nop 0
	s_nop 0
	s_nop 0
	s_nop 0
.Lkq_1:
	s_waitcnt vmcnt(0)
	s_barrier
	s_mov_b64 s[76:77], s[48:49]
	s_add_u32 vcc_lo, s80, 0xffffff80
	s_addc_u32 vcc_hi, s81, -1
	s_add_u32 s76, s76, 0x80
	s_addc_u32 s77, s77, 0
	s_add_u32 vcc_lo, vcc_lo, 0x80
	s_addc_u32 vcc_hi, vcc_hi, 0
	v_lshl_add_u64 v[136:137], s[76:77], 0, v[0:1]
	s_add_i32 m0, s94, 0x4000
	v_lshl_add_u64 v[144:145], s[76:77], 0, v[130:131]
	global_load_lds_dwordx4 v[136:137], off
	s_add_i32 m0, s94, 0x6000
	s_nop 0
	global_load_lds_dwordx4 v[144:145], off
	v_lshl_add_u64 v[182:183], vcc, 0, v[0:1]
	s_add_i32 m0, s93, 0x14000
	v_lshl_add_u64 v[236:237], vcc, 0, v[130:131]
	global_load_lds_dwordx4 v[182:183], off
	s_add_i32 m0, s93, 0x16000
	s_nop 0
	global_load_lds_dwordx4 v[236:237], off
	s_add_u32 s76, s76, 0x80
	s_addc_u32 s77, s77, 0
	s_add_u32 vcc_lo, vcc_lo, 0x80
	s_addc_u32 vcc_hi, vcc_hi, 0
	s_mov_b32 s82, 3
	s_add_i32 s59, s79, -1
	v_add_u32_e32 v136, 0x10000, v147
	ds_read_b128 v[148:151], v136
	ds_read_b128 v[152:155], v136 offset:1024
	ds_read_b128 v[156:159], v136 offset:2048
	ds_read_b128 v[160:163], v136 offset:3072
	ds_read_b128 v[202:205], v165
	ds_read_b128 v[208:211], v165 offset:1024
	ds_read_b128 v[212:215], v165 offset:2048
	ds_read_b128 v[216:219], v165 offset:3072
	ds_read_b128 v[220:223], v165 offset:4096
	ds_read_b128 v[224:227], v165 offset:5120
	ds_read_b128 v[228:231], v165 offset:6144
	ds_read_b128 v[232:235], v165 offset:7168
	v_lshl_add_u64 v[136:137], s[76:77], 0, v[0:1]
	s_add_i32 m0, s94, 0xc000
	v_lshl_add_u64 v[144:145], s[76:77], 0, v[130:131]
	global_load_lds_dwordx4 v[136:137], off
	s_add_i32 m0, s94, 0xe000
	s_nop 0
	global_load_lds_dwordx4 v[144:145], off
	v_lshl_add_u64 v[182:183], vcc, 0, v[0:1]
	s_add_i32 m0, s93, 0x1c000
	v_lshl_add_u64 v[236:237], vcc, 0, v[130:131]
	global_load_lds_dwordx4 v[182:183], off
	s_add_i32 m0, s93, 0x1e000
	s_nop 0
	global_load_lds_dwordx4 v[236:237], off
	s_cmp_lt_u32 s82, s59
	s_cselect_b32 s83, 0x80, 0
	s_add_u32 s76, s76, s83
	s_addc_u32 s77, s77, 0
	s_add_u32 vcc_lo, vcc_lo, s83
	s_addc_u32 vcc_hi, vcc_hi, 0
	s_add_i32 s82, s82, 1
	s_waitcnt vmcnt(8)
	s_waitcnt lgkmcnt(0)
	s_barrier
	s_setprio 1
	v_mfma_f32_16x16x32_bf16 v[126:129], v[148:151], v[202:205], 0
	v_mfma_f32_16x16x32_bf16 v[122:125], v[156:159], v[202:205], 0
	v_mfma_f32_16x16x32_bf16 v[110:113], v[148:151], v[212:215], 0
	v_mfma_f32_16x16x32_bf16 v[106:109], v[156:159], v[212:215], 0
	v_mfma_f32_16x16x32_bf16 v[94:97], v[148:151], v[220:223], 0
	v_mfma_f32_16x16x32_bf16 v[90:93], v[156:159], v[220:223], 0
	v_mfma_f32_16x16x32_bf16 v[78:81], v[148:151], v[228:231], 0
	v_mfma_f32_16x16x32_bf16 v[74:77], v[156:159], v[228:231], 0
	v_mfma_f32_16x16x32_bf16 v[126:129], v[152:155], v[208:211], v[126:129]
	v_mfma_f32_16x16x32_bf16 v[122:125], v[160:163], v[208:211], v[122:125]
	v_mfma_f32_16x16x32_bf16 v[110:113], v[152:155], v[216:219], v[110:113]
	v_mfma_f32_16x16x32_bf16 v[106:109], v[160:163], v[216:219], v[106:109]
	v_mfma_f32_16x16x32_bf16 v[94:97], v[152:155], v[224:227], v[94:97]
	v_mfma_f32_16x16x32_bf16 v[90:93], v[160:163], v[224:227], v[90:93]
	v_mfma_f32_16x16x32_bf16 v[78:81], v[152:155], v[232:235], v[78:81]
	v_mfma_f32_16x16x32_bf16 v[74:77], v[160:163], v[232:235], v[74:77]
	s_setprio 0
	s_barrier
; #define PG8_STAGE(bufoff, gbase, voff) do { _Pragma("unroll") for (int _i = 0; _i < 2; ++_i) \
;         __builtin_amdgcn_global_load_lds((const unsigned*)((const char*)(gbase) + (voff)[_i]), (PG8_LAS unsigned*)(lds + (bufoff) + ldsw + _i * 8192), 16, 0, 0); } while (0)
; #define PG8_LDA(dst, b, h) do { _Pragma("unroll") for (int m = 0; m < 4; ++m) _Pragma("unroll") for (int k = 0; k < 2; ++k) dst[m][k] = *(const PG8_LAS bf16x8*)(lds + PG8_SA(b, h) + aoff + m * 2048 + k * 1024); } while (0)
; #define PG8_LDB(dst, b, h) do { _Pragma("unroll") for (int n = 0; n < 2; ++n) _Pragma("unroll") for (int k = 0; k < 2; ++k) dst[n][k] = *(const PG8_LAS bf16x8*)(lds + PG8_SB(b, h) + boff + n * 2048 + k * 1024); } while (0)
; #define PG8_MMA(ai, bj, At, Bt) do { __builtin_amdgcn_s_setprio(1); _Pragma("unroll") for (int m = 0; m < 4; ++m) _Pragma("unroll") for (int n = 0; n < 2; ++n) _Pragma("unroll") for (int k = 0; k < 2; ++k) \
;         acc[ai][bj][m][n] = __builtin_amdgcn_mfma_f32_16x16x32_bf16(Bt[n][k], At[m][k], acc[ai][bj][m][n], 0, 0, 0); __builtin_amdgcn_s_setprio(0); } while (0)
; #define PG8_WAIT_V(n) asm volatile("s_waitcnt vmcnt(" #n ")" ::: "memory")
; template <class Epi, class Sched, bool ALIGN_EPI = false, bool SP2 = false>
; __device__ __forceinline__ void gemm_phase(PG8_LAS unsigned char* lds, const Gemm g, const Sched& S, const Epi& E) {
;     ...
;             PG8_LDB(B0, 0, 0); PG8_LDB(B1, 0, 1); PG8_SCHED; PG8_LDA(At, 0, 0); PG8_STAGE(PG8_SA(1, 1), a1 + hstep, voffA);
;             PG8_WAIT_V(8); PG8_WAIT_L(0); PG8_BAR; PG8_MMA(0, 0, At, B0); PG8_MMA(0, 1, At, B1); PG8_BAR; PG8_SCHED;
;             PG8_LDA(At, 0, 1); PG8_STAGE(PG8_SB(0, 0), b2, voffB); PG8_STAGE(PG8_SB(0, 1), b2 + hstep, voffB); PG8_STAGE(PG8_SA(0, 0), a2, voffA);
;             PG8_WAIT_V(8); PG8_WAIT_L(0); PG8_BAR; PG8_MMA(1, 0, At, B0); PG8_MMA(1, 1, At, B1); PG8_BAR; PG8_SCHED;
;             PG8_LDB(B0, 1, 0); PG8_LDB(B1, 1, 1); PG8_SCHED; PG8_LDA(At, 1, 0); PG8_STAGE(PG8_SA(0, 1), a2 + hstep, voffA);
;             PG8_WAIT_V(8); PG8_WAIT_L(0); PG8_BAR; PG8_MMA(0, 0, At, B0); PG8_MMA(0, 1, At, B1); PG8_BAR; PG8_SCHED;
;             PG8_LDA(At, 1, 1); PG8_STAGE(PG8_SB(1, 0), b3, voffB); PG8_STAGE(PG8_SB(1, 1), b3 + hstep, voffB); PG8_STAGE(PG8_SA(1, 0), a3, voffA);
;             PG8_WAIT_V(8); PG8_WAIT_L(0); PG8_BAR; PG8_MMA(1, 0, At, B0); PG8_MMA(1, 1, At, B1); PG8_BAR; PG8_SCHED;
	v_add_u32_e32 v136, 0x18000, v147
	ds_read_b128 v[148:151], v136
	ds_read_b128 v[152:155], v136 offset:1024
	ds_read_b128 v[156:159], v136 offset:2048
	ds_read_b128 v[160:163], v136 offset:3072
	ds_read_b128 v[202:205], v165 offset:32768
	ds_read_b128 v[208:211], v165 offset:33792
	ds_read_b128 v[212:215], v165 offset:34816
	ds_read_b128 v[216:219], v165 offset:35840
	ds_read_b128 v[220:223], v165 offset:36864
	ds_read_b128 v[224:227], v165 offset:37888
	ds_read_b128 v[228:231], v165 offset:38912
	ds_read_b128 v[232:235], v165 offset:39936
	v_lshl_add_u64 v[136:137], s[76:77], 0, v[0:1]
	s_add_i32 m0, s94, 0x0
	v_lshl_add_u64 v[144:145], s[76:77], 0, v[130:131]
	global_load_lds_dwordx4 v[136:137], off
	s_add_i32 m0, s94, 0x2000
	s_nop 0
	global_load_lds_dwordx4 v[144:145], off
	v_lshl_add_u64 v[182:183], vcc, 0, v[0:1]
	s_add_i32 m0, s93, 0x10000
	v_lshl_add_u64 v[236:237], vcc, 0, v[130:131]
	global_load_lds_dwordx4 v[182:183], off
	s_add_i32 m0, s93, 0x12000
	s_nop 0
	global_load_lds_dwordx4 v[236:237], off
	s_cmp_lt_u32 s82, s59
	s_cselect_b32 s83, 0x80, 0
	s_add_u32 s76, s76, s83
	s_addc_u32 s77, s77, 0
	s_add_u32 vcc_lo, vcc_lo, s83
	s_addc_u32 vcc_hi, vcc_hi, 0
	s_add_i32 s82, s82, 1
	s_waitcnt vmcnt(8)
	s_waitcnt lgkmcnt(0)
	s_barrier
	s_setprio 1
	v_mfma_f32_16x16x32_bf16 v[126:129], v[148:151], v[202:205], v[126:129]
	v_mfma_f32_16x16x32_bf16 v[122:125], v[156:159], v[202:205], v[122:125]
	v_mfma_f32_16x16x32_bf16 v[110:113], v[148:151], v[212:215], v[110:113]
	v_mfma_f32_16x16x32_bf16 v[106:109], v[156:159], v[212:215], v[106:109]
	v_mfma_f32_16x16x32_bf16 v[94:97], v[148:151], v[220:223], v[94:97]
	v_mfma_f32_16x16x32_bf16 v[90:93], v[156:159], v[220:223], v[90:93]
	v_mfma_f32_16x16x32_bf16 v[78:81], v[148:151], v[228:231], v[78:81]
	v_mfma_f32_16x16x32_bf16 v[74:77], v[156:159], v[228:231], v[74:77]
	v_mfma_f32_16x16x32_bf16 v[126:129], v[152:155], v[208:211], v[126:129]
	v_mfma_f32_16x16x32_bf16 v[122:125], v[160:163], v[208:211], v[122:125]
	v_mfma_f32_16x16x32_bf16 v[110:113], v[152:155], v[216:219], v[110:113]
	v_mfma_f32_16x16x32_bf16 v[106:109], v[160:163], v[216:219], v[106:109]
	v_mfma_f32_16x16x32_bf16 v[94:97], v[152:155], v[224:227], v[94:97]
	v_mfma_f32_16x16x32_bf16 v[90:93], v[160:163], v[224:227], v[90:93]
	v_mfma_f32_16x16x32_bf16 v[78:81], v[152:155], v[232:235], v[78:81]
	v_mfma_f32_16x16x32_bf16 v[74:77], v[160:163], v[232:235], v[74:77]
	s_setprio 0
	s_barrier
	v_add_u32_e32 v136, 0x14000, v147
	ds_read_b128 v[148:151], v136
	ds_read_b128 v[152:155], v136 offset:1024
	ds_read_b128 v[156:159], v136 offset:2048
	ds_read_b128 v[160:163], v136 offset:3072
	ds_read_b128 v[202:205], v165 offset:16384
	ds_read_b128 v[208:211], v165 offset:17408
	ds_read_b128 v[212:215], v165 offset:18432
	ds_read_b128 v[216:219], v165 offset:19456
	ds_read_b128 v[220:223], v165 offset:20480
	ds_read_b128 v[224:227], v165 offset:21504
	ds_read_b128 v[228:231], v165 offset:22528
	ds_read_b128 v[232:235], v165 offset:23552
	v_lshl_add_u64 v[136:137], s[76:77], 0, v[0:1]
	s_add_i32 m0, s94, 0x8000
	v_lshl_add_u64 v[144:145], s[76:77], 0, v[130:131]
	global_load_lds_dwordx4 v[136:137], off
	s_add_i32 m0, s94, 0xa000
	s_nop 0
	global_load_lds_dwordx4 v[144:145], off
	v_lshl_add_u64 v[182:183], vcc, 0, v[0:1]
	s_add_i32 m0, s93, 0x18000
	v_lshl_add_u64 v[236:237], vcc, 0, v[130:131]
	global_load_lds_dwordx4 v[182:183], off
	s_add_i32 m0, s93, 0x1a000
	s_nop 0
	global_load_lds_dwordx4 v[236:237], off
	s_cmp_lt_u32 s82, s59
	s_cselect_b32 s83, 0x80, 0
	s_add_u32 s76, s76, s83
	s_addc_u32 s77, s77, 0
	s_add_u32 vcc_lo, vcc_lo, s83
	s_addc_u32 vcc_hi, vcc_hi, 0
	s_add_i32 s82, s82, 1
	s_waitcnt vmcnt(8)
	s_waitcnt lgkmcnt(0)
	s_barrier
; #define PG8_STAGE(bufoff, gbase, voff) do { _Pragma("unroll") for (int _i = 0; _i < 2; ++_i) \
;         __builtin_amdgcn_global_load_lds((const unsigned*)((const char*)(gbase) + (voff)[_i]), (PG8_LAS unsigned*)(lds + (bufoff) + ldsw + _i * 8192), 16, 0, 0); } while (0)
; #define PG8_LDA(dst, b, h) do { _Pragma("unroll") for (int m = 0; m < 4; ++m) _Pragma("unroll") for (int k = 0; k < 2; ++k) dst[m][k] = *(const PG8_LAS bf16x8*)(lds + PG8_SA(b, h) + aoff + m * 2048 + k * 1024); } while (0)
; #define PG8_LDB(dst, b, h) do { _Pragma("unroll") for (int n = 0; n < 2; ++n) _Pragma("unroll") for (int k = 0; k < 2; ++k) dst[n][k] = *(const PG8_LAS bf16x8*)(lds + PG8_SB(b, h) + boff + n * 2048 + k * 1024); } while (0)
; #define PG8_MMA(ai, bj, At, Bt) do { __builtin_amdgcn_s_setprio(1); _Pragma("unroll") for (int m = 0; m < 4; ++m) _Pragma("unroll") for (int n = 0; n < 2; ++n) _Pragma("unroll") for (int k = 0; k < 2; ++k) \
;         acc[ai][bj][m][n] = __builtin_amdgcn_mfma_f32_16x16x32_bf16(Bt[n][k], At[m][k], acc[ai][bj][m][n], 0, 0, 0); __builtin_amdgcn_s_setprio(0); } while (0)
; #define PG8_WAIT_V(n) asm volatile("s_waitcnt vmcnt(" #n ")" ::: "memory")
; template <class Epi, class Sched, bool ALIGN_EPI = false, bool SP2 = false>
; __device__ __forceinline__ void gemm_phase(PG8_LAS unsigned char* lds, const Gemm g, const Sched& S, const Epi& E) {
;     ...
;             PG8_LDB(B0, 0, 0); PG8_LDB(B1, 0, 1); PG8_SCHED; PG8_LDA(At, 0, 0); PG8_STAGE(PG8_SA(1, 1), a1 + hstep, voffA);
;             PG8_WAIT_V(8); PG8_WAIT_L(0); PG8_BAR; PG8_MMA(0, 0, At, B0); PG8_MMA(0, 1, At, B1); PG8_BAR; PG8_SCHED;
;             PG8_LDA(At, 0, 1); PG8_STAGE(PG8_SB(0, 0), b2, voffB); PG8_STAGE(PG8_SB(0, 1), b2 + hstep, voffB); PG8_STAGE(PG8_SA(0, 0), a2, voffA);
;             PG8_WAIT_V(8); PG8_WAIT_L(0); PG8_BAR; PG8_MMA(1, 0, At, B0); PG8_MMA(1, 1, At, B1); PG8_BAR; PG8_SCHED;
;             PG8_LDB(B0, 1, 0); PG8_LDB(B1, 1, 1); PG8_SCHED; PG8_LDA(At, 1, 0); PG8_STAGE(PG8_SA(0, 1), a2 + hstep, voffA);
;             PG8_WAIT_V(8); PG8_WAIT_L(0); PG8_BAR; PG8_MMA(0, 0, At, B0); PG8_MMA(0, 1, At, B1); PG8_BAR; PG8_SCHED;
;             PG8_LDA(At, 1, 1); PG8_STAGE(PG8_SB(1, 0), b3, voffB); PG8_STAGE(PG8_SB(1, 1), b3 + hstep, voffB); PG8_STAGE(PG8_SA(1, 0), a3, voffA);
;             PG8_WAIT_V(8); PG8_WAIT_L(0); PG8_BAR; PG8_MMA(1, 0, At, B0); PG8_MMA(1, 1, At, B1); PG8_BAR; PG8_SCHED;
	s_setprio 1
	v_mfma_f32_16x16x32_bf16 v[126:129], v[148:151], v[202:205], v[126:129]
	v_mfma_f32_16x16x32_bf16 v[122:125], v[156:159], v[202:205], v[122:125]
	v_mfma_f32_16x16x32_bf16 v[110:113], v[148:151], v[212:215], v[110:113]
	v_mfma_f32_16x16x32_bf16 v[106:109], v[156:159], v[212:215], v[106:109]
	v_mfma_f32_16x16x32_bf16 v[94:97], v[148:151], v[220:223], v[94:97]
	v_mfma_f32_16x16x32_bf16 v[90:93], v[156:159], v[220:223], v[90:93]
	v_mfma_f32_16x16x32_bf16 v[78:81], v[148:151], v[228:231], v[78:81]
	v_mfma_f32_16x16x32_bf16 v[74:77], v[156:159], v[228:231], v[74:77]
	v_mfma_f32_16x16x32_bf16 v[126:129], v[152:155], v[208:211], v[126:129]
	v_mfma_f32_16x16x32_bf16 v[122:125], v[160:163], v[208:211], v[122:125]
	v_mfma_f32_16x16x32_bf16 v[110:113], v[152:155], v[216:219], v[110:113]
	v_mfma_f32_16x16x32_bf16 v[106:109], v[160:163], v[216:219], v[106:109]
	v_mfma_f32_16x16x32_bf16 v[94:97], v[152:155], v[224:227], v[94:97]
	v_mfma_f32_16x16x32_bf16 v[90:93], v[160:163], v[224:227], v[90:93]
	v_mfma_f32_16x16x32_bf16 v[78:81], v[152:155], v[232:235], v[78:81]
	v_mfma_f32_16x16x32_bf16 v[74:77], v[160:163], v[232:235], v[74:77]
	s_setprio 0
	s_barrier
	v_add_u32_e32 v136, 0x1c000, v147
	ds_read_b128 v[148:151], v136
	ds_read_b128 v[152:155], v136 offset:1024
	ds_read_b128 v[156:159], v136 offset:2048
	ds_read_b128 v[160:163], v136 offset:3072
	ds_read_b128 v[202:205], v165 offset:49152
	ds_read_b128 v[208:211], v165 offset:50176
	ds_read_b128 v[212:215], v165 offset:51200
	ds_read_b128 v[216:219], v165 offset:52224
	ds_read_b128 v[220:223], v165 offset:53248
	ds_read_b128 v[224:227], v165 offset:54272
	ds_read_b128 v[228:231], v165 offset:55296
	ds_read_b128 v[232:235], v165 offset:56320
	v_lshl_add_u64 v[136:137], s[76:77], 0, v[0:1]
	s_add_i32 m0, s94, 0x4000
	v_lshl_add_u64 v[144:145], s[76:77], 0, v[130:131]
	global_load_lds_dwordx4 v[136:137], off
	s_add_i32 m0, s94, 0x6000
	s_nop 0
	global_load_lds_dwordx4 v[144:145], off
	v_lshl_add_u64 v[182:183], vcc, 0, v[0:1]
	s_add_i32 m0, s93, 0x14000
	v_lshl_add_u64 v[236:237], vcc, 0, v[130:131]
	global_load_lds_dwordx4 v[182:183], off
	s_add_i32 m0, s93, 0x16000
	s_nop 0
	global_load_lds_dwordx4 v[236:237], off
	s_cmp_lt_u32 s82, s59
	s_cselect_b32 s83, 0x80, 0
	s_add_u32 s76, s76, s83
	s_addc_u32 s77, s77, 0
	s_add_u32 vcc_lo, vcc_lo, s83
	s_addc_u32 vcc_hi, vcc_hi, 0
	s_add_i32 s82, s82, 1
	s_waitcnt vmcnt(8)
	s_waitcnt lgkmcnt(0)
	s_barrier
	s_setprio 1
	v_mfma_f32_16x16x32_bf16 v[126:129], v[148:151], v[202:205], v[126:129]
	v_mfma_f32_16x16x32_bf16 v[122:125], v[156:159], v[202:205], v[122:125]
	v_mfma_f32_16x16x32_bf16 v[110:113], v[148:151], v[212:215], v[110:113]
	v_mfma_f32_16x16x32_bf16 v[106:109], v[156:159], v[212:215], v[106:109]
	v_mfma_f32_16x16x32_bf16 v[94:97], v[148:151], v[220:223], v[94:97]
	v_mfma_f32_16x16x32_bf16 v[90:93], v[156:159], v[220:223], v[90:93]
	v_mfma_f32_16x16x32_bf16 v[78:81], v[148:151], v[228:231], v[78:81]
	v_mfma_f32_16x16x32_bf16 v[74:77], v[156:159], v[228:231], v[74:77]
	v_mfma_f32_16x16x32_bf16 v[126:129], v[152:155], v[208:211], v[126:129]
	v_mfma_f32_16x16x32_bf16 v[122:125], v[160:163], v[208:211], v[122:125]
	v_mfma_f32_16x16x32_bf16 v[110:113], v[152:155], v[216:219], v[110:113]
	v_mfma_f32_16x16x32_bf16 v[106:109], v[160:163], v[216:219], v[106:109]
	v_mfma_f32_16x16x32_bf16 v[94:97], v[152:155], v[224:227], v[94:97]
	v_mfma_f32_16x16x32_bf16 v[90:93], v[160:163], v[224:227], v[90:93]
	v_mfma_f32_16x16x32_bf16 v[78:81], v[152:155], v[232:235], v[78:81]
	v_mfma_f32_16x16x32_bf16 v[74:77], v[160:163], v[232:235], v[74:77]
	s_setprio 0
	s_barrier
	s_add_i32 s83, s82, -3
	s_cmp_lt_u32 s83, s79
	s_cbranch_scc0 .Lkq_1_post

; #define PG8_STAGE(bufoff, gbase, voff) do { _Pragma("unroll") for (int _i = 0; _i < 2; ++_i) \
;         __builtin_amdgcn_global_load_lds((const unsigned*)((const char*)(gbase) + (voff)[_i]), (PG8_LAS unsigned*)(lds + (bufoff) + ldsw + _i * 8192), 16, 0, 0); } while (0)
; #define PG8_LDA(dst, b, h) do { _Pragma("unroll") for (int m = 0; m < 4; ++m) _Pragma("unroll") for (int k = 0; k < 2; ++k) dst[m][k] = *(const PG8_LAS bf16x8*)(lds + PG8_SA(b, h) + aoff + m * 2048 + k * 1024); } while (0)
; #define PG8_WAIT_V(n) asm volatile("s_waitcnt vmcnt(" #n ")" ::: "memory")
; #define PG8_WAIT_L(n) asm volatile("s_waitcnt lgkmcnt(" #n ")" ::: "memory")
; #define PG8_BAR __builtin_amdgcn_s_barrier()
; template <class Epi, class Sched, bool ALIGN_EPI = false, bool SP2 = false>
; __device__ __forceinline__ void gemm_phase(PG8_LAS unsigned char* lds, const Gemm g, const Sched& S, const Epi& E) {
;     ...
;         PG8_STAGE(PG8_SB(0, 0), cB, voffB); PG8_STAGE(PG8_SB(0, 1), cB + hstep, voffB); PG8_STAGE(PG8_SA(0, 0), cA, voffA); PG8_STAGE(PG8_SA(0, 1), cA + hstep, voffA);
;         if (wr == 1) PG8_BAR;
;         PG8_WAIT_V(2); PG8_BAR;
;         PG8_STAGE(PG8_SB(1, 0), cB + kstep, voffB); PG8_STAGE(PG8_SA(1, 0), cA + kstep, voffA); PG8_STAGE(PG8_SB(1, 1), cB + hstep + kstep, voffB);
;         PG8_WAIT_V(6); PG8_BAR;
;     ...
;             if constexpr (SP2) {
;             PG8_LDB(B0, 0, 0); PG8_LDB(B1, 0, 1); PG8_SCHED; PG8_LDA(At, 0, 0); PG8_STAGE(PG8_SA(1, 1), a1 + hstep, voffA);
;             PG8_WAIT_V(8); PG8_WAIT_L(0); PG8_BAR; PG8_MMA(0, 0, At, B0); PG8_MMA(0, 1, At, B1); PG8_BAR; PG8_SCHED;
;             PG8_LDA(At, 0, 1); PG8_STAGE(PG8_SB(0, 0), b2, voffB); PG8_STAGE(PG8_SB(0, 1), b2 + hstep, voffB); PG8_STAGE(PG8_SA(0, 0), a2, voffA);
;             PG8_WAIT_V(8); PG8_WAIT_L(0); PG8_BAR; PG8_MMA(1, 0, At, B0); PG8_MMA(1, 1, At, B1); PG8_BAR; PG8_SCHED;
;             PG8_LDB(B0, 1, 0); PG8_LDB(B1, 1, 1); PG8_SCHED; PG8_LDA(At, 1, 0); PG8_STAGE(PG8_SA(0, 1), a2 + hstep, voffA);
;             PG8_WAIT_V(8); PG8_WAIT_L(0); PG8_BAR; PG8_MMA(0, 0, At, B0); PG8_MMA(0, 1, At, B1); PG8_BAR; PG8_SCHED;
;             PG8_LDA(At, 1, 1); PG8_STAGE(PG8_SB(1, 0), b3, voffB); PG8_STAGE(PG8_SB(1, 1), b3 + hstep, voffB); PG8_STAGE(PG8_SA(1, 0), a3, voffA);
;             PG8_WAIT_V(8); PG8_WAIT_L(0); PG8_BAR; PG8_MMA(1, 0, At, B0); PG8_MMA(1, 1, At, B1); PG8_BAR; PG8_SCHED;
.Lkq_1_post:
	s_mov_b64 s[76:77], s[8:9]
	s_mov_b64 vcc, s[46:47]
	v_lshl_add_u64 v[136:137], vcc, 0, v[0:1]
	s_add_i32 m0, s93, 0x10000
	v_lshl_add_u64 v[144:145], vcc, 0, v[130:131]
	global_load_lds_dwordx4 v[136:137], off
	s_add_i32 m0, s93, 0x12000
	s_nop 0
	global_load_lds_dwordx4 v[144:145], off
	s_add_u32 vcc_lo, vcc_lo, s10
	s_addc_u32 vcc_hi, vcc_hi, 0
	v_lshl_add_u64 v[136:137], vcc, 0, v[0:1]
	s_add_i32 m0, s93, 0x14000
	v_lshl_add_u64 v[144:145], vcc, 0, v[130:131]
	global_load_lds_dwordx4 v[136:137], off
	s_add_i32 m0, s93, 0x16000
	s_nop 0
	global_load_lds_dwordx4 v[144:145], off
	v_lshl_add_u64 v[136:137], s[76:77], 0, v[0:1]
	s_add_i32 m0, s94, 0x0
	v_lshl_add_u64 v[144:145], s[76:77], 0, v[130:131]
	global_load_lds_dwordx4 v[136:137], off
	s_add_i32 m0, s94, 0x2000
	s_nop 0
	global_load_lds_dwordx4 v[144:145], off
	s_add_u32 s76, s76, s10
	s_addc_u32 s77, s77, 0
	v_lshl_add_u64 v[136:137], s[76:77], 0, v[0:1]
	s_add_i32 m0, s94, 0x4000
	v_lshl_add_u64 v[144:145], s[76:77], 0, v[130:131]
	global_load_lds_dwordx4 v[136:137], off
	s_add_i32 m0, s94, 0x6000
	s_nop 0
	global_load_lds_dwordx4 v[144:145], off
	s_add_u32 s76, s8, 0x80
	s_addc_u32 s77, s9, 0
	s_add_u32 vcc_lo, s46, 0x80
	s_addc_u32 vcc_hi, s47, 0
	v_lshl_add_u64 v[136:137], vcc, 0, v[0:1]
	s_add_i32 m0, s93, 0x18000
	v_lshl_add_u64 v[144:145], vcc, 0, v[130:131]
	global_load_lds_dwordx4 v[136:137], off
	s_add_i32 m0, s93, 0x1a000
	s_nop 0
	global_load_lds_dwordx4 v[144:145], off
	s_add_u32 vcc_lo, vcc_lo, s10
	s_addc_u32 vcc_hi, vcc_hi, 0
	v_lshl_add_u64 v[136:137], vcc, 0, v[0:1]
	s_add_i32 m0, s93, 0x1c000
	v_lshl_add_u64 v[144:145], vcc, 0, v[130:131]
	global_load_lds_dwordx4 v[136:137], off
	s_add_i32 m0, s93, 0x1e000
	s_nop 0
	global_load_lds_dwordx4 v[144:145], off
	v_lshl_add_u64 v[136:137], s[76:77], 0, v[0:1]
	s_add_i32 m0, s94, 0x8000
	v_lshl_add_u64 v[144:145], s[76:77], 0, v[130:131]
	global_load_lds_dwordx4 v[136:137], off
	s_add_i32 m0, s94, 0xa000
	s_nop 0
	global_load_lds_dwordx4 v[144:145], off
	s_branch .Lkq_exit
	s_nop 0
	s_nop 0
	s_nop 0
	s_nop 0
	s_nop 0
	s_nop 0
.Lkq_2:
	s_waitcnt vmcnt(0)
	s_barrier
	s_mov_b64 s[76:77], s[48:49]
	s_add_u32 vcc_lo, s80, 0xffffff80
	s_addc_u32 vcc_hi, s81, -1
	s_add_u32 s76, s76, s10
	s_addc_u32 s77, s77, 0
	v_lshl_add_u64 v[136:137], s[76:77], 0, v[0:1]
	s_add_i32 m0, s94, 0xc000
	v_lshl_add_u64 v[144:145], s[76:77], 0, v[130:131]
	global_load_lds_dwordx4 v[136:137], off
	s_add_i32 m0, s94, 0xe000
	s_nop 0
	global_load_lds_dwordx4 v[144:145], off
	s_add_u32 s76, s76, 0x80
	s_addc_u32 s77, s77, 0
	s_add_u32 vcc_lo, vcc_lo, 0x80
	s_addc_u32 vcc_hi, vcc_hi, 0
	v_lshl_add_u64 v[136:137], s[76:77], 0, v[0:1]
	s_add_i32 m0, s94, 0x0
	v_lshl_add_u64 v[144:145], s[76:77], 0, v[130:131]
	global_load_lds_dwordx4 v[136:137], off
	s_add_i32 m0, s94, 0x2000
	s_nop 0
	global_load_lds_dwordx4 v[144:145], off
	v_lshl_add_u64 v[182:183], vcc, 0, v[0:1]
	s_add_i32 m0, s93, 0x14000
	v_lshl_add_u64 v[236:237], vcc, 0, v[130:131]
	global_load_lds_dwordx4 v[182:183], off
	s_add_i32 m0, s93, 0x16000
	s_nop 0
	global_load_lds_dwordx4 v[236:237], off
	s_add_u32 s76, s76, 0x80
	s_addc_u32 s77, s77, 0
	s_add_u32 vcc_lo, vcc_lo, 0x80
	s_addc_u32 vcc_hi, vcc_hi, 0
	s_mov_b32 s82, 3
	s_add_i32 s59, s79, -1
	v_add_u32_e32 v136, 0x10000, v147
	ds_read_b128 v[148:151], v136
	ds_read_b128 v[152:155], v136 offset:1024
	ds_read_b128 v[156:159], v136 offset:2048
	ds_read_b128 v[160:163], v136 offset:3072
	ds_read_b128 v[202:205], v165 offset:16384
	ds_read_b128 v[208:211], v165 offset:17408
	ds_read_b128 v[212:215], v165 offset:18432
	ds_read_b128 v[216:219], v165 offset:19456
	ds_read_b128 v[220:223], v165 offset:20480
	ds_read_b128 v[224:227], v165 offset:21504
	ds_read_b128 v[228:231], v165 offset:22528
	ds_read_b128 v[232:235], v165 offset:23552
	v_lshl_add_u64 v[136:137], s[76:77], 0, v[0:1]
	s_add_i32 m0, s94, 0x8000
	v_lshl_add_u64 v[144:145], s[76:77], 0, v[130:131]
	global_load_lds_dwordx4 v[136:137], off
	s_add_i32 m0, s94, 0xa000
	s_nop 0
	global_load_lds_dwordx4 v[144:145], off
	v_lshl_add_u64 v[182:183], vcc, 0, v[0:1]
	s_add_i32 m0, s93, 0x1c000
	v_lshl_add_u64 v[236:237], vcc, 0, v[130:131]
	global_load_lds_dwordx4 v[182:183], off
	s_add_i32 m0, s93, 0x1e000
	s_nop 0
	global_load_lds_dwordx4 v[236:237], off
	s_cmp_lt_u32 s82, s59
	s_cselect_b32 s83, 0x80, 0
	s_add_u32 s76, s76, s83
	s_addc_u32 s77, s77, 0
	s_add_u32 vcc_lo, vcc_lo, s83
	s_addc_u32 vcc_hi, vcc_hi, 0
	s_add_i32 s82, s82, 1
	s_waitcnt vmcnt(8)
	s_waitcnt lgkmcnt(0)
	s_barrier
	s_setprio 1
	v_mfma_f32_16x16x32_bf16 v[62:65], v[148:151], v[202:205], 0
	v_mfma_f32_16x16x32_bf16 v[58:61], v[156:159], v[202:205], 0
	v_mfma_f32_16x16x32_bf16 v[46:49], v[148:151], v[212:215], 0
	v_mfma_f32_16x16x32_bf16 v[42:45], v[156:159], v[212:215], 0
	v_mfma_f32_16x16x32_bf16 v[30:33], v[148:151], v[220:223], 0
	v_mfma_f32_16x16x32_bf16 v[26:29], v[156:159], v[220:223], 0
	v_mfma_f32_16x16x32_bf16 v[14:17], v[148:151], v[228:231], 0
	v_mfma_f32_16x16x32_bf16 v[10:13], v[156:159], v[228:231], 0
	v_mfma_f32_16x16x32_bf16 v[62:65], v[152:155], v[208:211], v[62:65]
	v_mfma_f32_16x16x32_bf16 v[58:61], v[160:163], v[208:211], v[58:61]
	v_mfma_f32_16x16x32_bf16 v[46:49], v[152:155], v[216:219], v[46:49]
	v_mfma_f32_16x16x32_bf16 v[42:45], v[160:163], v[216:219], v[42:45]
	v_mfma_f32_16x16x32_bf16 v[30:33], v[152:155], v[224:227], v[30:33]
	v_mfma_f32_16x16x32_bf16 v[26:29], v[160:163], v[224:227], v[26:29]
	v_mfma_f32_16x16x32_bf16 v[14:17], v[152:155], v[232:235], v[14:17]
	v_mfma_f32_16x16x32_bf16 v[10:13], v[160:163], v[232:235], v[10:13]
	s_setprio 0
	s_barrier
; #define PG8_STAGE(bufoff, gbase, voff) do { _Pragma("unroll") for (int _i = 0; _i < 2; ++_i) \
;         __builtin_amdgcn_global_load_lds((const unsigned*)((const char*)(gbase) + (voff)[_i]), (PG8_LAS unsigned*)(lds + (bufoff) + ldsw + _i * 8192), 16, 0, 0); } while (0)
; #define PG8_LDA(dst, b, h) do { _Pragma("unroll") for (int m = 0; m < 4; ++m) _Pragma("unroll") for (int k = 0; k < 2; ++k) dst[m][k] = *(const PG8_LAS bf16x8*)(lds + PG8_SA(b, h) + aoff + m * 2048 + k * 1024); } while (0)
; #define PG8_LDB(dst, b, h) do { _Pragma("unroll") for (int n = 0; n < 2; ++n) _Pragma("unroll") for (int k = 0; k < 2; ++k) dst[n][k] = *(const PG8_LAS bf16x8*)(lds + PG8_SB(b, h) + boff + n * 2048 + k * 1024); } while (0)
; #define PG8_MMA(ai, bj, At, Bt) do { __builtin_amdgcn_s_setprio(1); _Pragma("unroll") for (int m = 0; m < 4; ++m) _Pragma("unroll") for (int n = 0; n < 2; ++n) _Pragma("unroll") for (int k = 0; k < 2; ++k) \
;         acc[ai][bj][m][n] = __builtin_amdgcn_mfma_f32_16x16x32_bf16(Bt[n][k], At[m][k], acc[ai][bj][m][n], 0, 0, 0); __builtin_amdgcn_s_setprio(0); } while (0)
; #define PG8_WAIT_V(n) asm volatile("s_waitcnt vmcnt(" #n ")" ::: "memory")
; template <class Epi, class Sched, bool ALIGN_EPI = false, bool SP2 = false>
; __device__ __forceinline__ void gemm_phase(PG8_LAS unsigned char* lds, const Gemm g, const Sched& S, const Epi& E) {
;     ...
;             PG8_LDB(B0, 0, 0); PG8_LDB(B1, 0, 1); PG8_SCHED; PG8_LDA(At, 0, 0); PG8_STAGE(PG8_SA(1, 1), a1 + hstep, voffA);
;             PG8_WAIT_V(8); PG8_WAIT_L(0); PG8_BAR; PG8_MMA(0, 0, At, B0); PG8_MMA(0, 1, At, B1); PG8_BAR; PG8_SCHED;
;             PG8_LDA(At, 0, 1); PG8_STAGE(PG8_SB(0, 0), b2, voffB); PG8_STAGE(PG8_SB(0, 1), b2 + hstep, voffB); PG8_STAGE(PG8_SA(0, 0), a2, voffA);
;             PG8_WAIT_V(8); PG8_WAIT_L(0); PG8_BAR; PG8_MMA(1, 0, At, B0); PG8_MMA(1, 1, At, B1); PG8_BAR; PG8_SCHED;
;             PG8_LDB(B0, 1, 0); PG8_LDB(B1, 1, 1); PG8_SCHED; PG8_LDA(At, 1, 0); PG8_STAGE(PG8_SA(0, 1), a2 + hstep, voffA);
;             PG8_WAIT_V(8); PG8_WAIT_L(0); PG8_BAR; PG8_MMA(0, 0, At, B0); PG8_MMA(0, 1, At, B1); PG8_BAR; PG8_SCHED;
;             PG8_LDA(At, 1, 1); PG8_STAGE(PG8_SB(1, 0), b3, voffB); PG8_STAGE(PG8_SB(1, 1), b3 + hstep, voffB); PG8_STAGE(PG8_SA(1, 0), a3, voffA);
;             PG8_WAIT_V(8); PG8_WAIT_L(0); PG8_BAR; PG8_MMA(1, 0, At, B0); PG8_MMA(1, 1, At, B1); PG8_BAR; PG8_SCHED;
	v_add_u32_e32 v136, 0x18000, v147
	ds_read_b128 v[148:151], v136
	ds_read_b128 v[152:155], v136 offset:1024
	ds_read_b128 v[156:159], v136 offset:2048
	ds_read_b128 v[160:163], v136 offset:3072
	ds_read_b128 v[202:205], v165 offset:49152
	ds_read_b128 v[208:211], v165 offset:50176
	ds_read_b128 v[212:215], v165 offset:51200
	ds_read_b128 v[216:219], v165 offset:52224
	ds_read_b128 v[220:223], v165 offset:53248
	ds_read_b128 v[224:227], v165 offset:54272
	ds_read_b128 v[228:231], v165 offset:55296
	ds_read_b128 v[232:235], v165 offset:56320
	v_lshl_add_u64 v[136:137], s[76:77], 0, v[0:1]
	s_add_i32 m0, s94, 0x4000
	v_lshl_add_u64 v[144:145], s[76:77], 0, v[130:131]
	global_load_lds_dwordx4 v[136:137], off
	s_add_i32 m0, s94, 0x6000
	s_nop 0
	global_load_lds_dwordx4 v[144:145], off
	v_lshl_add_u64 v[182:183], vcc, 0, v[0:1]
	s_add_i32 m0, s93, 0x10000
	v_lshl_add_u64 v[236:237], vcc, 0, v[130:131]
	global_load_lds_dwordx4 v[182:183], off
	s_add_i32 m0, s93, 0x12000
	s_nop 0
	global_load_lds_dwordx4 v[236:237], off
	s_cmp_lt_u32 s82, s59
	s_cselect_b32 s83, 0x80, 0
	s_add_u32 s76, s76, s83
	s_addc_u32 s77, s77, 0
	s_add_u32 vcc_lo, vcc_lo, s83
	s_addc_u32 vcc_hi, vcc_hi, 0
	s_add_i32 s82, s82, 1
	s_waitcnt vmcnt(8)
	s_waitcnt lgkmcnt(0)
	s_barrier
	s_setprio 1
	v_mfma_f32_16x16x32_bf16 v[62:65], v[148:151], v[202:205], v[62:65]
	v_mfma_f32_16x16x32_bf16 v[58:61], v[156:159], v[202:205], v[58:61]
	v_mfma_f32_16x16x32_bf16 v[46:49], v[148:151], v[212:215], v[46:49]
	v_mfma_f32_16x16x32_bf16 v[42:45], v[156:159], v[212:215], v[42:45]
	v_mfma_f32_16x16x32_bf16 v[30:33], v[148:151], v[220:223], v[30:33]
	v_mfma_f32_16x16x32_bf16 v[26:29], v[156:159], v[220:223], v[26:29]
	v_mfma_f32_16x16x32_bf16 v[14:17], v[148:151], v[228:231], v[14:17]
	v_mfma_f32_16x16x32_bf16 v[10:13], v[156:159], v[228:231], v[10:13]
	v_mfma_f32_16x16x32_bf16 v[62:65], v[152:155], v[208:211], v[62:65]
	v_mfma_f32_16x16x32_bf16 v[58:61], v[160:163], v[208:211], v[58:61]
	v_mfma_f32_16x16x32_bf16 v[46:49], v[152:155], v[216:219], v[46:49]
	v_mfma_f32_16x16x32_bf16 v[42:45], v[160:163], v[216:219], v[42:45]
	v_mfma_f32_16x16x32_bf16 v[30:33], v[152:155], v[224:227], v[30:33]
	v_mfma_f32_16x16x32_bf16 v[26:29], v[160:163], v[224:227], v[26:29]
	v_mfma_f32_16x16x32_bf16 v[14:17], v[152:155], v[232:235], v[14:17]
	v_mfma_f32_16x16x32_bf16 v[10:13], v[160:163], v[232:235], v[10:13]
	s_setprio 0
	s_barrier
	v_add_u32_e32 v136, 0x14000, v147
	ds_read_b128 v[148:151], v136
	ds_read_b128 v[152:155], v136 offset:1024
	ds_read_b128 v[156:159], v136 offset:2048
	ds_read_b128 v[160:163], v136 offset:3072
	ds_read_b128 v[202:205], v165
	ds_read_b128 v[208:211], v165 offset:1024
	ds_read_b128 v[212:215], v165 offset:2048
	ds_read_b128 v[216:219], v165 offset:3072
	ds_read_b128 v[220:223], v165 offset:4096
	ds_read_b128 v[224:227], v165 offset:5120
	ds_read_b128 v[228:231], v165 offset:6144
	ds_read_b128 v[232:235], v165 offset:7168
	v_lshl_add_u64 v[136:137], s[76:77], 0, v[0:1]
	s_add_i32 m0, s94, 0xc000
	v_lshl_add_u64 v[144:145], s[76:77], 0, v[130:131]
	global_load_lds_dwordx4 v[136:137], off
	s_add_i32 m0, s94, 0xe000
	s_nop 0
	global_load_lds_dwordx4 v[144:145], off
	v_lshl_add_u64 v[182:183], vcc, 0, v[0:1]
	s_add_i32 m0, s93, 0x18000
	v_lshl_add_u64 v[236:237], vcc, 0, v[130:131]
	global_load_lds_dwordx4 v[182:183], off
	s_add_i32 m0, s93, 0x1a000
	s_nop 0
	global_load_lds_dwordx4 v[236:237], off
	s_cmp_lt_u32 s82, s59
	s_cselect_b32 s83, 0x80, 0
	s_add_u32 s76, s76, s83
	s_addc_u32 s77, s77, 0
	s_add_u32 vcc_lo, vcc_lo, s83
	s_addc_u32 vcc_hi, vcc_hi, 0
	s_add_i32 s82, s82, 1
	s_waitcnt vmcnt(8)
	s_waitcnt lgkmcnt(0)
	s_barrier
; #define PG8_STAGE(bufoff, gbase, voff) do { _Pragma("unroll") for (int _i = 0; _i < 2; ++_i) \
;         __builtin_amdgcn_global_load_lds((const unsigned*)((const char*)(gbase) + (voff)[_i]), (PG8_LAS unsigned*)(lds + (bufoff) + ldsw + _i * 8192), 16, 0, 0); } while (0)
; #define PG8_LDA(dst, b, h) do { _Pragma("unroll") for (int m = 0; m < 4; ++m) _Pragma("unroll") for (int k = 0; k < 2; ++k) dst[m][k] = *(const PG8_LAS bf16x8*)(lds + PG8_SA(b, h) + aoff + m * 2048 + k * 1024); } while (0)
; #define PG8_LDB(dst, b, h) do { _Pragma("unroll") for (int n = 0; n < 2; ++n) _Pragma("unroll") for (int k = 0; k < 2; ++k) dst[n][k] = *(const PG8_LAS bf16x8*)(lds + PG8_SB(b, h) + boff + n * 2048 + k * 1024); } while (0)
; #define PG8_MMA(ai, bj, At, Bt) do { __builtin_amdgcn_s_setprio(1); _Pragma("unroll") for (int m = 0; m < 4; ++m) _Pragma("unroll") for (int n = 0; n < 2; ++n) _Pragma("unroll") for (int k = 0; k < 2; ++k) \
;         acc[ai][bj][m][n] = __builtin_amdgcn_mfma_f32_16x16x32_bf16(Bt[n][k], At[m][k], acc[ai][bj][m][n], 0, 0, 0); __builtin_amdgcn_s_setprio(0); } while (0)
; #define PG8_WAIT_V(n) asm volatile("s_waitcnt vmcnt(" #n ")" ::: "memory")
; template <class Epi, class Sched, bool ALIGN_EPI = false, bool SP2 = false>
; __device__ __forceinline__ void gemm_phase(PG8_LAS unsigned char* lds, const Gemm g, const Sched& S, const Epi& E) {
;     ...
;             PG8_LDB(B0, 0, 0); PG8_LDB(B1, 0, 1); PG8_SCHED; PG8_LDA(At, 0, 0); PG8_STAGE(PG8_SA(1, 1), a1 + hstep, voffA);
;             PG8_WAIT_V(8); PG8_WAIT_L(0); PG8_BAR; PG8_MMA(0, 0, At, B0); PG8_MMA(0, 1, At, B1); PG8_BAR; PG8_SCHED;
;             PG8_LDA(At, 0, 1); PG8_STAGE(PG8_SB(0, 0), b2, voffB); PG8_STAGE(PG8_SB(0, 1), b2 + hstep, voffB); PG8_STAGE(PG8_SA(0, 0), a2, voffA);
;             PG8_WAIT_V(8); PG8_WAIT_L(0); PG8_BAR; PG8_MMA(1, 0, At, B0); PG8_MMA(1, 1, At, B1); PG8_BAR; PG8_SCHED;
;             PG8_LDB(B0, 1, 0); PG8_LDB(B1, 1, 1); PG8_SCHED; PG8_LDA(At, 1, 0); PG8_STAGE(PG8_SA(0, 1), a2 + hstep, voffA);
;             PG8_WAIT_V(8); PG8_WAIT_L(0); PG8_BAR; PG8_MMA(0, 0, At, B0); PG8_MMA(0, 1, At, B1); PG8_BAR; PG8_SCHED;
;             PG8_LDA(At, 1, 1); PG8_STAGE(PG8_SB(1, 0), b3, voffB); PG8_STAGE(PG8_SB(1, 1), b3 + hstep, voffB); PG8_STAGE(PG8_SA(1, 0), a3, voffA);
;             PG8_WAIT_V(8); PG8_WAIT_L(0); PG8_BAR; PG8_MMA(1, 0, At, B0); PG8_MMA(1, 1, At, B1); PG8_BAR; PG8_SCHED;
	s_setprio 1
	v_mfma_f32_16x16x32_bf16 v[62:65], v[148:151], v[202:205], v[62:65]
	v_mfma_f32_16x16x32_bf16 v[58:61], v[156:159], v[202:205], v[58:61]
	v_mfma_f32_16x16x32_bf16 v[46:49], v[148:151], v[212:215], v[46:49]
	v_mfma_f32_16x16x32_bf16 v[42:45], v[156:159], v[212:215], v[42:45]
	v_mfma_f32_16x16x32_bf16 v[30:33], v[148:151], v[220:223], v[30:33]
	v_mfma_f32_16x16x32_bf16 v[26:29], v[156:159], v[220:223], v[26:29]
	v_mfma_f32_16x16x32_bf16 v[14:17], v[148:151], v[228:231], v[14:17]
	v_mfma_f32_16x16x32_bf16 v[10:13], v[156:159], v[228:231], v[10:13]
	v_mfma_f32_16x16x32_bf16 v[62:65], v[152:155], v[208:211], v[62:65]
	v_mfma_f32_16x16x32_bf16 v[58:61], v[160:163], v[208:211], v[58:61]
	v_mfma_f32_16x16x32_bf16 v[46:49], v[152:155], v[216:219], v[46:49]
	v_mfma_f32_16x16x32_bf16 v[42:45], v[160:163], v[216:219], v[42:45]
	v_mfma_f32_16x16x32_bf16 v[30:33], v[152:155], v[224:227], v[30:33]
	v_mfma_f32_16x16x32_bf16 v[26:29], v[160:163], v[224:227], v[26:29]
	v_mfma_f32_16x16x32_bf16 v[14:17], v[152:155], v[232:235], v[14:17]
	v_mfma_f32_16x16x32_bf16 v[10:13], v[160:163], v[232:235], v[10:13]
	s_setprio 0
	s_barrier
	v_add_u32_e32 v136, 0x1c000, v147
	ds_read_b128 v[148:151], v136
	ds_read_b128 v[152:155], v136 offset:1024
	ds_read_b128 v[156:159], v136 offset:2048
	ds_read_b128 v[160:163], v136 offset:3072
	ds_read_b128 v[202:205], v165 offset:32768
	ds_read_b128 v[208:211], v165 offset:33792
	ds_read_b128 v[212:215], v165 offset:34816
	ds_read_b128 v[216:219], v165 offset:35840
	ds_read_b128 v[220:223], v165 offset:36864
	ds_read_b128 v[224:227], v165 offset:37888
	ds_read_b128 v[228:231], v165 offset:38912
	ds_read_b128 v[232:235], v165 offset:39936
	v_lshl_add_u64 v[136:137], s[76:77], 0, v[0:1]
	s_add_i32 m0, s94, 0x0
	v_lshl_add_u64 v[144:145], s[76:77], 0, v[130:131]
	global_load_lds_dwordx4 v[136:137], off
	s_add_i32 m0, s94, 0x2000
	s_nop 0
	global_load_lds_dwordx4 v[144:145], off
	v_lshl_add_u64 v[182:183], vcc, 0, v[0:1]
	s_add_i32 m0, s93, 0x14000
	v_lshl_add_u64 v[236:237], vcc, 0, v[130:131]
	global_load_lds_dwordx4 v[182:183], off
	s_add_i32 m0, s93, 0x16000
	s_nop 0
	global_load_lds_dwordx4 v[236:237], off
	s_cmp_lt_u32 s82, s59
	s_cselect_b32 s83, 0x80, 0
	s_add_u32 s76, s76, s83
	s_addc_u32 s77, s77, 0
	s_add_u32 vcc_lo, vcc_lo, s83
	s_addc_u32 vcc_hi, vcc_hi, 0
	s_add_i32 s82, s82, 1
	s_waitcnt vmcnt(8)
	s_waitcnt lgkmcnt(0)
	s_barrier
	s_setprio 1
	v_mfma_f32_16x16x32_bf16 v[62:65], v[148:151], v[202:205], v[62:65]
	v_mfma_f32_16x16x32_bf16 v[58:61], v[156:159], v[202:205], v[58:61]
	v_mfma_f32_16x16x32_bf16 v[46:49], v[148:151], v[212:215], v[46:49]
	v_mfma_f32_16x16x32_bf16 v[42:45], v[156:159], v[212:215], v[42:45]
	v_mfma_f32_16x16x32_bf16 v[30:33], v[148:151], v[220:223], v[30:33]
	v_mfma_f32_16x16x32_bf16 v[26:29], v[156:159], v[220:223], v[26:29]
	v_mfma_f32_16x16x32_bf16 v[14:17], v[148:151], v[228:231], v[14:17]
	v_mfma_f32_16x16x32_bf16 v[10:13], v[156:159], v[228:231], v[10:13]
	v_mfma_f32_16x16x32_bf16 v[62:65], v[152:155], v[208:211], v[62:65]
	v_mfma_f32_16x16x32_bf16 v[58:61], v[160:163], v[208:211], v[58:61]
	v_mfma_f32_16x16x32_bf16 v[46:49], v[152:155], v[216:219], v[46:49]
	v_mfma_f32_16x16x32_bf16 v[42:45], v[160:163], v[216:219], v[42:45]
	v_mfma_f32_16x16x32_bf16 v[30:33], v[152:155], v[224:227], v[30:33]
	v_mfma_f32_16x16x32_bf16 v[26:29], v[160:163], v[224:227], v[26:29]
	v_mfma_f32_16x16x32_bf16 v[14:17], v[152:155], v[232:235], v[14:17]
	v_mfma_f32_16x16x32_bf16 v[10:13], v[160:163], v[232:235], v[10:13]
	s_setprio 0
	s_barrier
	s_add_i32 s83, s82, -3
	s_cmp_lt_u32 s83, s79
	s_cbranch_scc0 .Lkq_2_post

; #define PG8_STAGE(bufoff, gbase, voff) do { _Pragma("unroll") for (int _i = 0; _i < 2; ++_i) \
;         __builtin_amdgcn_global_load_lds((const unsigned*)((const char*)(gbase) + (voff)[_i]), (PG8_LAS unsigned*)(lds + (bufoff) + ldsw + _i * 8192), 16, 0, 0); } while (0)
; #define PG8_LDA(dst, b, h) do { _Pragma("unroll") for (int m = 0; m < 4; ++m) _Pragma("unroll") for (int k = 0; k < 2; ++k) dst[m][k] = *(const PG8_LAS bf16x8*)(lds + PG8_SA(b, h) + aoff + m * 2048 + k * 1024); } while (0)
; #define PG8_LDB(dst, b, h) do { _Pragma("unroll") for (int n = 0; n < 2; ++n) _Pragma("unroll") for (int k = 0; k < 2; ++k) dst[n][k] = *(const PG8_LAS bf16x8*)(lds + PG8_SB(b, h) + boff + n * 2048 + k * 1024); } while (0)
; #define PG8_WAIT_V(n) asm volatile("s_waitcnt vmcnt(" #n ")" ::: "memory")
; #define PG8_WAIT_L(n) asm volatile("s_waitcnt lgkmcnt(" #n ")" ::: "memory")
; template <class Epi, class Sched, bool ALIGN_EPI = false, bool SP2 = false>
; __device__ __forceinline__ void gemm_phase(PG8_LAS unsigned char* lds, const Gemm g, const Sched& S, const Epi& E) {
;     ...
; #pragma unroll
;     for (int a = 0; a < 2; ++a)
; #pragma unroll
;         for (int b = 0; b < 2; ++b)
; #pragma unroll
;             for (int m = 0; m < 4; ++m)
; #pragma unroll
;                 for (int n = 0; n < 2; ++n) acc[a][b][m][n] = (f32x4){0.f, 0.f, 0.f, 0.f};
;     ...
;             PG8_LDB(B0, 0, 0); PG8_LDB(B1, 0, 1); PG8_SCHED; PG8_LDA(At, 0, 0); PG8_STAGE(PG8_SA(1, 1), a1 + hstep, voffA);
;             PG8_WAIT_V(8); PG8_WAIT_L(0); PG8_BAR; PG8_MMA(0, 0, At, B0); PG8_MMA(0, 1, At, B1); PG8_BAR; PG8_SCHED;
;             PG8_LDA(At, 0, 1); PG8_STAGE(PG8_SB(0, 0), b2, voffB); PG8_STAGE(PG8_SB(0, 1), b2 + hstep, voffB); PG8_STAGE(PG8_SA(0, 0), a2, voffA);
;             PG8_WAIT_V(8); PG8_WAIT_L(0); PG8_BAR; PG8_MMA(1, 0, At, B0); PG8_MMA(1, 1, At, B1); PG8_BAR; PG8_SCHED;
;             PG8_LDB(B0, 1, 0); PG8_LDB(B1, 1, 1); PG8_SCHED; PG8_LDA(At, 1, 0); PG8_STAGE(PG8_SA(0, 1), a2 + hstep, voffA);
;             PG8_WAIT_V(8); PG8_WAIT_L(0); PG8_BAR; PG8_MMA(0, 0, At, B0); PG8_MMA(0, 1, At, B1); PG8_BAR; PG8_SCHED;
;             PG8_LDA(At, 1, 1); PG8_STAGE(PG8_SB(1, 0), b3, voffB); PG8_STAGE(PG8_SB(1, 1), b3 + hstep, voffB); PG8_STAGE(PG8_SA(1, 0), a3, voffA);
;             PG8_WAIT_V(8); PG8_WAIT_L(0); PG8_BAR; PG8_MMA(1, 0, At, B0); PG8_MMA(1, 1, At, B1); PG8_BAR; PG8_SCHED;
.Lkq_3:
	s_waitcnt vmcnt(0)
	s_barrier
	s_mov_b64 s[76:77], s[48:49]
	s_add_u32 vcc_lo, s80, 0xffffff80
	s_addc_u32 vcc_hi, s81, -1
	s_add_u32 vcc_lo, vcc_lo, s10
	s_addc_u32 vcc_hi, vcc_hi, 0
	s_add_u32 s76, s76, 0x80
	s_addc_u32 s77, s77, 0
	s_add_u32 vcc_lo, vcc_lo, 0x80
	s_addc_u32 vcc_hi, vcc_hi, 0
	v_lshl_add_u64 v[136:137], s[76:77], 0, v[0:1]
	s_add_i32 m0, s94, 0x4000
	v_lshl_add_u64 v[144:145], s[76:77], 0, v[130:131]
	global_load_lds_dwordx4 v[136:137], off
	s_add_i32 m0, s94, 0x6000
	s_nop 0
	global_load_lds_dwordx4 v[144:145], off
	v_lshl_add_u64 v[182:183], vcc, 0, v[0:1]
	s_add_i32 m0, s93, 0x10000
	v_lshl_add_u64 v[236:237], vcc, 0, v[130:131]
	global_load_lds_dwordx4 v[182:183], off
	s_add_i32 m0, s93, 0x12000
	s_nop 0
	global_load_lds_dwordx4 v[236:237], off
	s_add_u32 s76, s76, 0x80
	s_addc_u32 s77, s77, 0
	s_add_u32 vcc_lo, vcc_lo, 0x80
	s_addc_u32 vcc_hi, vcc_hi, 0
	s_mov_b32 s82, 3
	s_add_i32 s59, s79, -1
	v_add_u32_e32 v136, 0x14000, v147
	ds_read_b128 v[166:169], v136
	ds_read_b128 v[170:173], v136 offset:1024
	ds_read_b128 v[174:177], v136 offset:2048
	ds_read_b128 v[178:181], v136 offset:3072
	ds_read_b128 v[202:205], v165
	ds_read_b128 v[208:211], v165 offset:1024
	ds_read_b128 v[212:215], v165 offset:2048
	ds_read_b128 v[216:219], v165 offset:3072
	ds_read_b128 v[220:223], v165 offset:4096
	ds_read_b128 v[224:227], v165 offset:5120
	ds_read_b128 v[228:231], v165 offset:6144
	ds_read_b128 v[232:235], v165 offset:7168
	v_lshl_add_u64 v[136:137], s[76:77], 0, v[0:1]
	s_add_i32 m0, s94, 0xc000
	v_lshl_add_u64 v[144:145], s[76:77], 0, v[130:131]
	global_load_lds_dwordx4 v[136:137], off
	s_add_i32 m0, s94, 0xe000
	s_nop 0
	global_load_lds_dwordx4 v[144:145], off
	v_lshl_add_u64 v[182:183], vcc, 0, v[0:1]
	s_add_i32 m0, s93, 0x18000
	v_lshl_add_u64 v[236:237], vcc, 0, v[130:131]
	global_load_lds_dwordx4 v[182:183], off
	s_add_i32 m0, s93, 0x1a000
	s_nop 0
	global_load_lds_dwordx4 v[236:237], off
	s_cmp_lt_u32 s82, s59
	s_cselect_b32 s83, 0x80, 0
	s_add_u32 s76, s76, s83
	s_addc_u32 s77, s77, 0
	s_add_u32 vcc_lo, vcc_lo, s83
	s_addc_u32 vcc_hi, vcc_hi, 0
	s_add_i32 s82, s82, 1
	s_waitcnt vmcnt(8)
	s_waitcnt lgkmcnt(0)
	s_barrier
	s_setprio 1
	v_mfma_f32_16x16x32_bf16 v[118:121], v[166:169], v[202:205], 0
	v_mfma_f32_16x16x32_bf16 v[114:117], v[174:177], v[202:205], 0
	v_mfma_f32_16x16x32_bf16 v[102:105], v[166:169], v[212:215], 0
	v_mfma_f32_16x16x32_bf16 v[98:101], v[174:177], v[212:215], 0
	v_mfma_f32_16x16x32_bf16 v[86:89], v[166:169], v[220:223], 0
	v_mfma_f32_16x16x32_bf16 v[82:85], v[174:177], v[220:223], 0
	v_mfma_f32_16x16x32_bf16 v[70:73], v[166:169], v[228:231], 0
	v_mfma_f32_16x16x32_bf16 v[66:69], v[174:177], v[228:231], 0
	v_mfma_f32_16x16x32_bf16 v[118:121], v[170:173], v[208:211], v[118:121]
	v_mfma_f32_16x16x32_bf16 v[114:117], v[178:181], v[208:211], v[114:117]
	v_mfma_f32_16x16x32_bf16 v[102:105], v[170:173], v[216:219], v[102:105]
	v_mfma_f32_16x16x32_bf16 v[98:101], v[178:181], v[216:219], v[98:101]
	v_mfma_f32_16x16x32_bf16 v[86:89], v[170:173], v[224:227], v[86:89]
	v_mfma_f32_16x16x32_bf16 v[82:85], v[178:181], v[224:227], v[82:85]
	v_mfma_f32_16x16x32_bf16 v[70:73], v[170:173], v[232:235], v[70:73]
	v_mfma_f32_16x16x32_bf16 v[66:69], v[178:181], v[232:235], v[66:69]
	s_setprio 0
	s_barrier
	v_add_u32_e32 v136, 0x1c000, v147
	ds_read_b128 v[166:169], v136
	ds_read_b128 v[170:173], v136 offset:1024
	ds_read_b128 v[174:177], v136 offset:2048
	ds_read_b128 v[178:181], v136 offset:3072
	ds_read_b128 v[202:205], v165 offset:32768
	ds_read_b128 v[208:211], v165 offset:33792
	ds_read_b128 v[212:215], v165 offset:34816
	ds_read_b128 v[216:219], v165 offset:35840
	ds_read_b128 v[220:223], v165 offset:36864
	ds_read_b128 v[224:227], v165 offset:37888
	ds_read_b128 v[228:231], v165 offset:38912
	ds_read_b128 v[232:235], v165 offset:39936
	v_lshl_add_u64 v[136:137], s[76:77], 0, v[0:1]
	s_add_i32 m0, s94, 0x0
	v_lshl_add_u64 v[144:145], s[76:77], 0, v[130:131]
	global_load_lds_dwordx4 v[136:137], off
	s_add_i32 m0, s94, 0x2000
	s_nop 0
	global_load_lds_dwordx4 v[144:145], off
	v_lshl_add_u64 v[182:183], vcc, 0, v[0:1]
	s_add_i32 m0, s93, 0x14000
	v_lshl_add_u64 v[236:237], vcc, 0, v[130:131]
	global_load_lds_dwordx4 v[182:183], off
	s_add_i32 m0, s93, 0x16000
	s_nop 0
	global_load_lds_dwordx4 v[236:237], off
	s_cmp_lt_u32 s82, s59
	s_cselect_b32 s83, 0x80, 0
	s_add_u32 s76, s76, s83
	s_addc_u32 s77, s77, 0
	s_add_u32 vcc_lo, vcc_lo, s83
	s_addc_u32 vcc_hi, vcc_hi, 0
	s_add_i32 s82, s82, 1
	s_waitcnt vmcnt(8)
	s_waitcnt lgkmcnt(0)
	s_barrier
	s_setprio 1
	v_mfma_f32_16x16x32_bf16 v[118:121], v[166:169], v[202:205], v[118:121]
	v_mfma_f32_16x16x32_bf16 v[114:117], v[174:177], v[202:205], v[114:117]
	v_mfma_f32_16x16x32_bf16 v[102:105], v[166:169], v[212:215], v[102:105]
	v_mfma_f32_16x16x32_bf16 v[98:101], v[174:177], v[212:215], v[98:101]
	v_mfma_f32_16x16x32_bf16 v[86:89], v[166:169], v[220:223], v[86:89]
	v_mfma_f32_16x16x32_bf16 v[82:85], v[174:177], v[220:223], v[82:85]
	v_mfma_f32_16x16x32_bf16 v[70:73], v[166:169], v[228:231], v[70:73]
	v_mfma_f32_16x16x32_bf16 v[66:69], v[174:177], v[228:231], v[66:69]
	v_mfma_f32_16x16x32_bf16 v[118:121], v[170:173], v[208:211], v[118:121]
	v_mfma_f32_16x16x32_bf16 v[114:117], v[178:181], v[208:211], v[114:117]
	v_mfma_f32_16x16x32_bf16 v[102:105], v[170:173], v[216:219], v[102:105]
	v_mfma_f32_16x16x32_bf16 v[98:101], v[178:181], v[216:219], v[98:101]
	v_mfma_f32_16x16x32_bf16 v[86:89], v[170:173], v[224:227], v[86:89]
	v_mfma_f32_16x16x32_bf16 v[82:85], v[178:181], v[224:227], v[82:85]
	v_mfma_f32_16x16x32_bf16 v[70:73], v[170:173], v[232:235], v[70:73]
	v_mfma_f32_16x16x32_bf16 v[66:69], v[178:181], v[232:235], v[66:69]
	s_setprio 0
	s_barrier
; #define PG8_STAGE(bufoff, gbase, voff) do { _Pragma("unroll") for (int _i = 0; _i < 2; ++_i) \
;         __builtin_amdgcn_global_load_lds((const unsigned*)((const char*)(gbase) + (voff)[_i]), (PG8_LAS unsigned*)(lds + (bufoff) + ldsw + _i * 8192), 16, 0, 0); } while (0)
; #define PG8_LDA(dst, b, h) do { _Pragma("unroll") for (int m = 0; m < 4; ++m) _Pragma("unroll") for (int k = 0; k < 2; ++k) dst[m][k] = *(const PG8_LAS bf16x8*)(lds + PG8_SA(b, h) + aoff + m * 2048 + k * 1024); } while (0)
; #define PG8_LDB(dst, b, h) do { _Pragma("unroll") for (int n = 0; n < 2; ++n) _Pragma("unroll") for (int k = 0; k < 2; ++k) dst[n][k] = *(const PG8_LAS bf16x8*)(lds + PG8_SB(b, h) + boff + n * 2048 + k * 1024); } while (0)
; #define PG8_MMA(ai, bj, At, Bt) do { __builtin_amdgcn_s_setprio(1); _Pragma("unroll") for (int m = 0; m < 4; ++m) _Pragma("unroll") for (int n = 0; n < 2; ++n) _Pragma("unroll") for (int k = 0; k < 2; ++k) \
;         acc[ai][bj][m][n] = __builtin_amdgcn_mfma_f32_16x16x32_bf16(Bt[n][k], At[m][k], acc[ai][bj][m][n], 0, 0, 0); __builtin_amdgcn_s_setprio(0); } while (0)
; #define PG8_WAIT_V(n) asm volatile("s_waitcnt vmcnt(" #n ")" ::: "memory")
; template <class Epi, class Sched, bool ALIGN_EPI = false, bool SP2 = false>
; __device__ __forceinline__ void gemm_phase(PG8_LAS unsigned char* lds, const Gemm g, const Sched& S, const Epi& E) {
;     ...
;             PG8_LDB(B0, 0, 0); PG8_LDB(B1, 0, 1); PG8_SCHED; PG8_LDA(At, 0, 0); PG8_STAGE(PG8_SA(1, 1), a1 + hstep, voffA);
;             PG8_WAIT_V(8); PG8_WAIT_L(0); PG8_BAR; PG8_MMA(0, 0, At, B0); PG8_MMA(0, 1, At, B1); PG8_BAR; PG8_SCHED;
;             PG8_LDA(At, 0, 1); PG8_STAGE(PG8_SB(0, 0), b2, voffB); PG8_STAGE(PG8_SB(0, 1), b2 + hstep, voffB); PG8_STAGE(PG8_SA(0, 0), a2, voffA);
;             PG8_WAIT_V(8); PG8_WAIT_L(0); PG8_BAR; PG8_MMA(1, 0, At, B0); PG8_MMA(1, 1, At, B1); PG8_BAR; PG8_SCHED;
;             PG8_LDB(B0, 1, 0); PG8_LDB(B1, 1, 1); PG8_SCHED; PG8_LDA(At, 1, 0); PG8_STAGE(PG8_SA(0, 1), a2 + hstep, voffA);
;             PG8_WAIT_V(8); PG8_WAIT_L(0); PG8_BAR; PG8_MMA(0, 0, At, B0); PG8_MMA(0, 1, At, B1); PG8_BAR; PG8_SCHED;
;             PG8_LDA(At, 1, 1); PG8_STAGE(PG8_SB(1, 0), b3, voffB); PG8_STAGE(PG8_SB(1, 1), b3 + hstep, voffB); PG8_STAGE(PG8_SA(1, 0), a3, voffA);
;             PG8_WAIT_V(8); PG8_WAIT_L(0); PG8_BAR; PG8_MMA(1, 0, At, B0); PG8_MMA(1, 1, At, B1); PG8_BAR; PG8_SCHED;
	v_add_u32_e32 v136, 0x10000, v147
	ds_read_b128 v[166:169], v136
	ds_read_b128 v[170:173], v136 offset:1024
	ds_read_b128 v[174:177], v136 offset:2048
	ds_read_b128 v[178:181], v136 offset:3072
	ds_read_b128 v[202:205], v165 offset:16384
	ds_read_b128 v[208:211], v165 offset:17408
	ds_read_b128 v[212:215], v165 offset:18432
	ds_read_b128 v[216:219], v165 offset:19456
	ds_read_b128 v[220:223], v165 offset:20480
	ds_read_b128 v[224:227], v165 offset:21504
	ds_read_b128 v[228:231], v165 offset:22528
	ds_read_b128 v[232:235], v165 offset:23552
	v_lshl_add_u64 v[136:137], s[76:77], 0, v[0:1]
	s_add_i32 m0, s94, 0x8000
	v_lshl_add_u64 v[144:145], s[76:77], 0, v[130:131]
	global_load_lds_dwordx4 v[136:137], off
	s_add_i32 m0, s94, 0xa000
	s_nop 0
	global_load_lds_dwordx4 v[144:145], off
	v_lshl_add_u64 v[182:183], vcc, 0, v[0:1]
	s_add_i32 m0, s93, 0x1c000
	v_lshl_add_u64 v[236:237], vcc, 0, v[130:131]
	global_load_lds_dwordx4 v[182:183], off
	s_add_i32 m0, s93, 0x1e000
	s_nop 0
	global_load_lds_dwordx4 v[236:237], off
	s_cmp_lt_u32 s82, s59
	s_cselect_b32 s83, 0x80, 0
	s_add_u32 s76, s76, s83
	s_addc_u32 s77, s77, 0
	s_add_u32 vcc_lo, vcc_lo, s83
	s_addc_u32 vcc_hi, vcc_hi, 0
	s_add_i32 s82, s82, 1
	s_waitcnt vmcnt(8)
	s_waitcnt lgkmcnt(0)
	s_barrier
	s_setprio 1
	v_mfma_f32_16x16x32_bf16 v[118:121], v[166:169], v[202:205], v[118:121]
	v_mfma_f32_16x16x32_bf16 v[114:117], v[174:177], v[202:205], v[114:117]
	v_mfma_f32_16x16x32_bf16 v[102:105], v[166:169], v[212:215], v[102:105]
	v_mfma_f32_16x16x32_bf16 v[98:101], v[174:177], v[212:215], v[98:101]
	v_mfma_f32_16x16x32_bf16 v[86:89], v[166:169], v[220:223], v[86:89]
	v_mfma_f32_16x16x32_bf16 v[82:85], v[174:177], v[220:223], v[82:85]
	v_mfma_f32_16x16x32_bf16 v[70:73], v[166:169], v[228:231], v[70:73]
	v_mfma_f32_16x16x32_bf16 v[66:69], v[174:177], v[228:231], v[66:69]
	v_mfma_f32_16x16x32_bf16 v[118:121], v[170:173], v[208:211], v[118:121]
	v_mfma_f32_16x16x32_bf16 v[114:117], v[178:181], v[208:211], v[114:117]
	v_mfma_f32_16x16x32_bf16 v[102:105], v[170:173], v[216:219], v[102:105]
	v_mfma_f32_16x16x32_bf16 v[98:101], v[178:181], v[216:219], v[98:101]
	v_mfma_f32_16x16x32_bf16 v[86:89], v[170:173], v[224:227], v[86:89]
	v_mfma_f32_16x16x32_bf16 v[82:85], v[178:181], v[224:227], v[82:85]
	v_mfma_f32_16x16x32_bf16 v[70:73], v[170:173], v[232:235], v[70:73]
	v_mfma_f32_16x16x32_bf16 v[66:69], v[178:181], v[232:235], v[66:69]
	s_setprio 0
	s_barrier
	v_add_u32_e32 v136, 0x18000, v147
	ds_read_b128 v[166:169], v136
	ds_read_b128 v[170:173], v136 offset:1024
	ds_read_b128 v[174:177], v136 offset:2048
	ds_read_b128 v[178:181], v136 offset:3072
	ds_read_b128 v[202:205], v165 offset:49152
	ds_read_b128 v[208:211], v165 offset:50176
	ds_read_b128 v[212:215], v165 offset:51200
	ds_read_b128 v[216:219], v165 offset:52224
	ds_read_b128 v[220:223], v165 offset:53248
	ds_read_b128 v[224:227], v165 offset:54272
	ds_read_b128 v[228:231], v165 offset:55296
	ds_read_b128 v[232:235], v165 offset:56320
	v_lshl_add_u64 v[136:137], s[76:77], 0, v[0:1]
	s_add_i32 m0, s94, 0x4000
	v_lshl_add_u64 v[144:145], s[76:77], 0, v[130:131]
	global_load_lds_dwordx4 v[136:137], off
	s_add_i32 m0, s94, 0x6000
	s_nop 0
	global_load_lds_dwordx4 v[144:145], off
	v_lshl_add_u64 v[182:183], vcc, 0, v[0:1]
	s_add_i32 m0, s93, 0x10000
	v_lshl_add_u64 v[236:237], vcc, 0, v[130:131]
	global_load_lds_dwordx4 v[182:183], off
	s_add_i32 m0, s93, 0x12000
	s_nop 0
	global_load_lds_dwordx4 v[236:237], off
	s_cmp_lt_u32 s82, s59
	s_cselect_b32 s83, 0x80, 0
	s_add_u32 s76, s76, s83
	s_addc_u32 s77, s77, 0
	s_add_u32 vcc_lo, vcc_lo, s83
	s_addc_u32 vcc_hi, vcc_hi, 0
	s_add_i32 s82, s82, 1
	s_waitcnt vmcnt(8)
	s_waitcnt lgkmcnt(0)
	s_barrier
	s_setprio 1
	v_mfma_f32_16x16x32_bf16 v[118:121], v[166:169], v[202:205], v[118:121]
	v_mfma_f32_16x16x32_bf16 v[114:117], v[174:177], v[202:205], v[114:117]
	v_mfma_f32_16x16x32_bf16 v[102:105], v[166:169], v[212:215], v[102:105]
	v_mfma_f32_16x16x32_bf16 v[98:101], v[174:177], v[212:215], v[98:101]
	v_mfma_f32_16x16x32_bf16 v[86:89], v[166:169], v[220:223], v[86:89]
	v_mfma_f32_16x16x32_bf16 v[82:85], v[174:177], v[220:223], v[82:85]
	v_mfma_f32_16x16x32_bf16 v[70:73], v[166:169], v[228:231], v[70:73]
	v_mfma_f32_16x16x32_bf16 v[66:69], v[174:177], v[228:231], v[66:69]
	v_mfma_f32_16x16x32_bf16 v[118:121], v[170:173], v[208:211], v[118:121]
	v_mfma_f32_16x16x32_bf16 v[114:117], v[178:181], v[208:211], v[114:117]
	v_mfma_f32_16x16x32_bf16 v[102:105], v[170:173], v[216:219], v[102:105]
	v_mfma_f32_16x16x32_bf16 v[98:101], v[178:181], v[216:219], v[98:101]
	v_mfma_f32_16x16x32_bf16 v[86:89], v[170:173], v[224:227], v[86:89]
	v_mfma_f32_16x16x32_bf16 v[82:85], v[178:181], v[224:227], v[82:85]
	v_mfma_f32_16x16x32_bf16 v[70:73], v[170:173], v[232:235], v[70:73]
	v_mfma_f32_16x16x32_bf16 v[66:69], v[178:181], v[232:235], v[66:69]
	s_setprio 0
	s_barrier
	s_add_i32 s83, s82, -3
	s_cmp_lt_u32 s83, s79
	s_cbranch_scc0 .Lkq_3_post

; #define PG8_STAGE(bufoff, gbase, voff) do { _Pragma("unroll") for (int _i = 0; _i < 2; ++_i) \
;         __builtin_amdgcn_global_load_lds((const unsigned*)((const char*)(gbase) + (voff)[_i]), (PG8_LAS unsigned*)(lds + (bufoff) + ldsw + _i * 8192), 16, 0, 0); } while (0)
; #define PG8_LDA(dst, b, h) do { _Pragma("unroll") for (int m = 0; m < 4; ++m) _Pragma("unroll") for (int k = 0; k < 2; ++k) dst[m][k] = *(const PG8_LAS bf16x8*)(lds + PG8_SA(b, h) + aoff + m * 2048 + k * 1024); } while (0)
; #define PG8_LDB(dst, b, h) do { _Pragma("unroll") for (int n = 0; n < 2; ++n) _Pragma("unroll") for (int k = 0; k < 2; ++k) dst[n][k] = *(const PG8_LAS bf16x8*)(lds + PG8_SB(b, h) + boff + n * 2048 + k * 1024); } while (0)
; #define PG8_WAIT_V(n) asm volatile("s_waitcnt vmcnt(" #n ")" ::: "memory")
; #define PG8_WAIT_L(n) asm volatile("s_waitcnt lgkmcnt(" #n ")" ::: "memory")
; template <class Epi, class Sched, bool ALIGN_EPI = false, bool SP2 = false>
; __device__ __forceinline__ void gemm_phase(PG8_LAS unsigned char* lds, const Gemm g, const Sched& S, const Epi& E) {
;     ...
; #pragma unroll
;     for (int a = 0; a < 2; ++a)
; #pragma unroll
;         for (int b = 0; b < 2; ++b)
; #pragma unroll
;             for (int m = 0; m < 4; ++m)
; #pragma unroll
;                 for (int n = 0; n < 2; ++n) acc[a][b][m][n] = (f32x4){0.f, 0.f, 0.f, 0.f};
;     ...
;             PG8_LDB(B0, 0, 0); PG8_LDB(B1, 0, 1); PG8_SCHED; PG8_LDA(At, 0, 0); PG8_STAGE(PG8_SA(1, 1), a1 + hstep, voffA);
;             PG8_WAIT_V(8); PG8_WAIT_L(0); PG8_BAR; PG8_MMA(0, 0, At, B0); PG8_MMA(0, 1, At, B1); PG8_BAR; PG8_SCHED;
;             PG8_LDA(At, 0, 1); PG8_STAGE(PG8_SB(0, 0), b2, voffB); PG8_STAGE(PG8_SB(0, 1), b2 + hstep, voffB); PG8_STAGE(PG8_SA(0, 0), a2, voffA);
;             PG8_WAIT_V(8); PG8_WAIT_L(0); PG8_BAR; PG8_MMA(1, 0, At, B0); PG8_MMA(1, 1, At, B1); PG8_BAR; PG8_SCHED;
;             PG8_LDB(B0, 1, 0); PG8_LDB(B1, 1, 1); PG8_SCHED; PG8_LDA(At, 1, 0); PG8_STAGE(PG8_SA(0, 1), a2 + hstep, voffA);
;             PG8_WAIT_V(8); PG8_WAIT_L(0); PG8_BAR; PG8_MMA(0, 0, At, B0); PG8_MMA(0, 1, At, B1); PG8_BAR; PG8_SCHED;
;             PG8_LDA(At, 1, 1); PG8_STAGE(PG8_SB(1, 0), b3, voffB); PG8_STAGE(PG8_SB(1, 1), b3 + hstep, voffB); PG8_STAGE(PG8_SA(1, 0), a3, voffA);
;             PG8_WAIT_V(8); PG8_WAIT_L(0); PG8_BAR; PG8_MMA(1, 0, At, B0); PG8_MMA(1, 1, At, B1); PG8_BAR; PG8_SCHED;
.Lkq_4:
	s_waitcnt vmcnt(0)
	s_barrier
	s_mov_b64 s[76:77], s[48:49]
	s_add_u32 vcc_lo, s80, 0xffffff80
	s_addc_u32 vcc_hi, s81, -1
	s_add_u32 s76, s76, s10
	s_addc_u32 s77, s77, 0
	s_add_u32 vcc_lo, vcc_lo, s10
	s_addc_u32 vcc_hi, vcc_hi, 0
	v_lshl_add_u64 v[136:137], s[76:77], 0, v[0:1]
	s_add_i32 m0, s94, 0xc000
	v_lshl_add_u64 v[144:145], s[76:77], 0, v[130:131]
	global_load_lds_dwordx4 v[136:137], off
	s_add_i32 m0, s94, 0xe000
	s_nop 0
	global_load_lds_dwordx4 v[144:145], off
	s_add_u32 s76, s76, 0x80
	s_addc_u32 s77, s77, 0
	s_add_u32 vcc_lo, vcc_lo, 0x80
	s_addc_u32 vcc_hi, vcc_hi, 0
	v_lshl_add_u64 v[136:137], s[76:77], 0, v[0:1]
	s_add_i32 m0, s94, 0x0
	v_lshl_add_u64 v[144:145], s[76:77], 0, v[130:131]
	global_load_lds_dwordx4 v[136:137], off
	s_add_i32 m0, s94, 0x2000
	s_nop 0
	global_load_lds_dwordx4 v[144:145], off
	v_lshl_add_u64 v[182:183], vcc, 0, v[0:1]
	s_add_i32 m0, s93, 0x10000
	v_lshl_add_u64 v[236:237], vcc, 0, v[130:131]
	global_load_lds_dwordx4 v[182:183], off
	s_add_i32 m0, s93, 0x12000
	s_nop 0
	global_load_lds_dwordx4 v[236:237], off
	s_add_u32 s76, s76, 0x80
	s_addc_u32 s77, s77, 0
	s_add_u32 vcc_lo, vcc_lo, 0x80
	s_addc_u32 vcc_hi, vcc_hi, 0
	s_mov_b32 s82, 3
	s_add_i32 s59, s79, -1
	v_add_u32_e32 v136, 0x14000, v147
	ds_read_b128 v[166:169], v136
	ds_read_b128 v[170:173], v136 offset:1024
	ds_read_b128 v[174:177], v136 offset:2048
	ds_read_b128 v[178:181], v136 offset:3072
	ds_read_b128 v[202:205], v165 offset:16384
	ds_read_b128 v[208:211], v165 offset:17408
	ds_read_b128 v[212:215], v165 offset:18432
	ds_read_b128 v[216:219], v165 offset:19456
	ds_read_b128 v[220:223], v165 offset:20480
	ds_read_b128 v[224:227], v165 offset:21504
	ds_read_b128 v[228:231], v165 offset:22528
	ds_read_b128 v[232:235], v165 offset:23552
	v_lshl_add_u64 v[136:137], s[76:77], 0, v[0:1]
	s_add_i32 m0, s94, 0x8000
	v_lshl_add_u64 v[144:145], s[76:77], 0, v[130:131]
	global_load_lds_dwordx4 v[136:137], off
	s_add_i32 m0, s94, 0xa000
	s_nop 0
	global_load_lds_dwordx4 v[144:145], off
	v_lshl_add_u64 v[182:183], vcc, 0, v[0:1]
	s_add_i32 m0, s93, 0x18000
	v_lshl_add_u64 v[236:237], vcc, 0, v[130:131]
	global_load_lds_dwordx4 v[182:183], off
	s_add_i32 m0, s93, 0x1a000
	s_nop 0
	global_load_lds_dwordx4 v[236:237], off
	s_cmp_lt_u32 s82, s59
	s_cselect_b32 s83, 0x80, 0
	s_add_u32 s76, s76, s83
	s_addc_u32 s77, s77, 0
	s_add_u32 vcc_lo, vcc_lo, s83
	s_addc_u32 vcc_hi, vcc_hi, 0
	s_add_i32 s82, s82, 1
	s_waitcnt vmcnt(8)
	s_waitcnt lgkmcnt(0)
	s_barrier
	s_setprio 1
	v_mfma_f32_16x16x32_bf16 v[54:57], v[166:169], v[202:205], 0
	v_mfma_f32_16x16x32_bf16 v[50:53], v[174:177], v[202:205], 0
	v_mfma_f32_16x16x32_bf16 v[38:41], v[166:169], v[212:215], 0
	v_mfma_f32_16x16x32_bf16 v[34:37], v[174:177], v[212:215], 0
	v_mfma_f32_16x16x32_bf16 v[22:25], v[166:169], v[220:223], 0
	v_mfma_f32_16x16x32_bf16 v[18:21], v[174:177], v[220:223], 0
	v_mfma_f32_16x16x32_bf16 v[6:9], v[166:169], v[228:231], 0
	v_mfma_f32_16x16x32_bf16 v[2:5], v[174:177], v[228:231], 0
	v_mfma_f32_16x16x32_bf16 v[54:57], v[170:173], v[208:211], v[54:57]
	v_mfma_f32_16x16x32_bf16 v[50:53], v[178:181], v[208:211], v[50:53]
	v_mfma_f32_16x16x32_bf16 v[38:41], v[170:173], v[216:219], v[38:41]
	v_mfma_f32_16x16x32_bf16 v[34:37], v[178:181], v[216:219], v[34:37]
	v_mfma_f32_16x16x32_bf16 v[22:25], v[170:173], v[224:227], v[22:25]
	v_mfma_f32_16x16x32_bf16 v[18:21], v[178:181], v[224:227], v[18:21]
	v_mfma_f32_16x16x32_bf16 v[6:9], v[170:173], v[232:235], v[6:9]
	v_mfma_f32_16x16x32_bf16 v[2:5], v[178:181], v[232:235], v[2:5]
	s_setprio 0
	s_barrier
	v_add_u32_e32 v136, 0x1c000, v147
	ds_read_b128 v[166:169], v136
	ds_read_b128 v[170:173], v136 offset:1024
	ds_read_b128 v[174:177], v136 offset:2048
	ds_read_b128 v[178:181], v136 offset:3072
	ds_read_b128 v[202:205], v165 offset:49152
	ds_read_b128 v[208:211], v165 offset:50176
	ds_read_b128 v[212:215], v165 offset:51200
	ds_read_b128 v[216:219], v165 offset:52224
	ds_read_b128 v[220:223], v165 offset:53248
	ds_read_b128 v[224:227], v165 offset:54272
	ds_read_b128 v[228:231], v165 offset:55296
	ds_read_b128 v[232:235], v165 offset:56320
	v_lshl_add_u64 v[136:137], s[76:77], 0, v[0:1]
	s_add_i32 m0, s94, 0x4000
	v_lshl_add_u64 v[144:145], s[76:77], 0, v[130:131]
	global_load_lds_dwordx4 v[136:137], off
	s_add_i32 m0, s94, 0x6000
	s_nop 0
	global_load_lds_dwordx4 v[144:145], off
	v_lshl_add_u64 v[182:183], vcc, 0, v[0:1]
	s_add_i32 m0, s93, 0x14000
	v_lshl_add_u64 v[236:237], vcc, 0, v[130:131]
	global_load_lds_dwordx4 v[182:183], off
	s_add_i32 m0, s93, 0x16000
	s_nop 0
	global_load_lds_dwordx4 v[236:237], off
	s_cmp_lt_u32 s82, s59
	s_cselect_b32 s83, 0x80, 0
	s_add_u32 s76, s76, s83
	s_addc_u32 s77, s77, 0
	s_add_u32 vcc_lo, vcc_lo, s83
	s_addc_u32 vcc_hi, vcc_hi, 0
	s_add_i32 s82, s82, 1
	s_waitcnt vmcnt(8)
	s_waitcnt lgkmcnt(0)
	s_barrier
; #define PG8_STAGE(bufoff, gbase, voff) do { _Pragma("unroll") for (int _i = 0; _i < 2; ++_i) \
;         __builtin_amdgcn_global_load_lds((const unsigned*)((const char*)(gbase) + (voff)[_i]), (PG8_LAS unsigned*)(lds + (bufoff) + ldsw + _i * 8192), 16, 0, 0); } while (0)
; #define PG8_LDA(dst, b, h) do { _Pragma("unroll") for (int m = 0; m < 4; ++m) _Pragma("unroll") for (int k = 0; k < 2; ++k) dst[m][k] = *(const PG8_LAS bf16x8*)(lds + PG8_SA(b, h) + aoff + m * 2048 + k * 1024); } while (0)
; #define PG8_LDB(dst, b, h) do { _Pragma("unroll") for (int n = 0; n < 2; ++n) _Pragma("unroll") for (int k = 0; k < 2; ++k) dst[n][k] = *(const PG8_LAS bf16x8*)(lds + PG8_SB(b, h) + boff + n * 2048 + k * 1024); } while (0)
; #define PG8_MMA(ai, bj, At, Bt) do { __builtin_amdgcn_s_setprio(1); _Pragma("unroll") for (int m = 0; m < 4; ++m) _Pragma("unroll") for (int n = 0; n < 2; ++n) _Pragma("unroll") for (int k = 0; k < 2; ++k) \
;         acc[ai][bj][m][n] = __builtin_amdgcn_mfma_f32_16x16x32_bf16(Bt[n][k], At[m][k], acc[ai][bj][m][n], 0, 0, 0); __builtin_amdgcn_s_setprio(0); } while (0)
; #define PG8_WAIT_V(n) asm volatile("s_waitcnt vmcnt(" #n ")" ::: "memory")
; template <class Epi, class Sched, bool ALIGN_EPI = false, bool SP2 = false>
; __device__ __forceinline__ void gemm_phase(PG8_LAS unsigned char* lds, const Gemm g, const Sched& S, const Epi& E) {
;     ...
;             PG8_LDB(B0, 0, 0); PG8_LDB(B1, 0, 1); PG8_SCHED; PG8_LDA(At, 0, 0); PG8_STAGE(PG8_SA(1, 1), a1 + hstep, voffA);
;             PG8_WAIT_V(8); PG8_WAIT_L(0); PG8_BAR; PG8_MMA(0, 0, At, B0); PG8_MMA(0, 1, At, B1); PG8_BAR; PG8_SCHED;
;             PG8_LDA(At, 0, 1); PG8_STAGE(PG8_SB(0, 0), b2, voffB); PG8_STAGE(PG8_SB(0, 1), b2 + hstep, voffB); PG8_STAGE(PG8_SA(0, 0), a2, voffA);
;             PG8_WAIT_V(8); PG8_WAIT_L(0); PG8_BAR; PG8_MMA(1, 0, At, B0); PG8_MMA(1, 1, At, B1); PG8_BAR; PG8_SCHED;
;             PG8_LDB(B0, 1, 0); PG8_LDB(B1, 1, 1); PG8_SCHED; PG8_LDA(At, 1, 0); PG8_STAGE(PG8_SA(0, 1), a2 + hstep, voffA);
;             PG8_WAIT_V(8); PG8_WAIT_L(0); PG8_BAR; PG8_MMA(0, 0, At, B0); PG8_MMA(0, 1, At, B1); PG8_BAR; PG8_SCHED;
;             PG8_LDA(At, 1, 1); PG8_STAGE(PG8_SB(1, 0), b3, voffB); PG8_STAGE(PG8_SB(1, 1), b3 + hstep, voffB); PG8_STAGE(PG8_SA(1, 0), a3, voffA);
;             PG8_WAIT_V(8); PG8_WAIT_L(0); PG8_BAR; PG8_MMA(1, 0, At, B0); PG8_MMA(1, 1, At, B1); PG8_BAR; PG8_SCHED;
	s_setprio 1
	v_mfma_f32_16x16x32_bf16 v[54:57], v[166:169], v[202:205], v[54:57]
	v_mfma_f32_16x16x32_bf16 v[50:53], v[174:177], v[202:205], v[50:53]
	v_mfma_f32_16x16x32_bf16 v[38:41], v[166:169], v[212:215], v[38:41]
	v_mfma_f32_16x16x32_bf16 v[34:37], v[174:177], v[212:215], v[34:37]
	v_mfma_f32_16x16x32_bf16 v[22:25], v[166:169], v[220:223], v[22:25]
	v_mfma_f32_16x16x32_bf16 v[18:21], v[174:177], v[220:223], v[18:21]
	v_mfma_f32_16x16x32_bf16 v[6:9], v[166:169], v[228:231], v[6:9]
	v_mfma_f32_16x16x32_bf16 v[2:5], v[174:177], v[228:231], v[2:5]
	v_mfma_f32_16x16x32_bf16 v[54:57], v[170:173], v[208:211], v[54:57]
	v_mfma_f32_16x16x32_bf16 v[50:53], v[178:181], v[208:211], v[50:53]
	v_mfma_f32_16x16x32_bf16 v[38:41], v[170:173], v[216:219], v[38:41]
	v_mfma_f32_16x16x32_bf16 v[34:37], v[178:181], v[216:219], v[34:37]
	v_mfma_f32_16x16x32_bf16 v[22:25], v[170:173], v[224:227], v[22:25]
	v_mfma_f32_16x16x32_bf16 v[18:21], v[178:181], v[224:227], v[18:21]
	v_mfma_f32_16x16x32_bf16 v[6:9], v[170:173], v[232:235], v[6:9]
	v_mfma_f32_16x16x32_bf16 v[2:5], v[178:181], v[232:235], v[2:5]
	s_setprio 0
	s_barrier
	v_add_u32_e32 v136, 0x10000, v147
	ds_read_b128 v[166:169], v136
	ds_read_b128 v[170:173], v136 offset:1024
	ds_read_b128 v[174:177], v136 offset:2048
	ds_read_b128 v[178:181], v136 offset:3072
	ds_read_b128 v[202:205], v165
	ds_read_b128 v[208:211], v165 offset:1024
	ds_read_b128 v[212:215], v165 offset:2048
	ds_read_b128 v[216:219], v165 offset:3072
	ds_read_b128 v[220:223], v165 offset:4096
	ds_read_b128 v[224:227], v165 offset:5120
	ds_read_b128 v[228:231], v165 offset:6144
	ds_read_b128 v[232:235], v165 offset:7168
	v_lshl_add_u64 v[136:137], s[76:77], 0, v[0:1]
	s_add_i32 m0, s94, 0xc000
	v_lshl_add_u64 v[144:145], s[76:77], 0, v[130:131]
	global_load_lds_dwordx4 v[136:137], off
	s_add_i32 m0, s94, 0xe000
	s_nop 0
	global_load_lds_dwordx4 v[144:145], off
	v_lshl_add_u64 v[182:183], vcc, 0, v[0:1]
	s_add_i32 m0, s93, 0x1c000
	v_lshl_add_u64 v[236:237], vcc, 0, v[130:131]
	global_load_lds_dwordx4 v[182:183], off
	s_add_i32 m0, s93, 0x1e000
	s_nop 0
	global_load_lds_dwordx4 v[236:237], off
	s_cmp_lt_u32 s82, s59
	s_cselect_b32 s83, 0x80, 0
	s_add_u32 s76, s76, s83
	s_addc_u32 s77, s77, 0
	s_add_u32 vcc_lo, vcc_lo, s83
	s_addc_u32 vcc_hi, vcc_hi, 0
	s_add_i32 s82, s82, 1
	s_waitcnt vmcnt(8)
	s_waitcnt lgkmcnt(0)
	s_barrier
	s_setprio 1
	v_mfma_f32_16x16x32_bf16 v[54:57], v[166:169], v[202:205], v[54:57]
	v_mfma_f32_16x16x32_bf16 v[50:53], v[174:177], v[202:205], v[50:53]
	v_mfma_f32_16x16x32_bf16 v[38:41], v[166:169], v[212:215], v[38:41]
	v_mfma_f32_16x16x32_bf16 v[34:37], v[174:177], v[212:215], v[34:37]
	v_mfma_f32_16x16x32_bf16 v[22:25], v[166:169], v[220:223], v[22:25]
	v_mfma_f32_16x16x32_bf16 v[18:21], v[174:177], v[220:223], v[18:21]
	v_mfma_f32_16x16x32_bf16 v[6:9], v[166:169], v[228:231], v[6:9]
	v_mfma_f32_16x16x32_bf16 v[2:5], v[174:177], v[228:231], v[2:5]
	v_mfma_f32_16x16x32_bf16 v[54:57], v[170:173], v[208:211], v[54:57]
	v_mfma_f32_16x16x32_bf16 v[50:53], v[178:181], v[208:211], v[50:53]
	v_mfma_f32_16x16x32_bf16 v[38:41], v[170:173], v[216:219], v[38:41]
	v_mfma_f32_16x16x32_bf16 v[34:37], v[178:181], v[216:219], v[34:37]
	v_mfma_f32_16x16x32_bf16 v[22:25], v[170:173], v[224:227], v[22:25]
	v_mfma_f32_16x16x32_bf16 v[18:21], v[178:181], v[224:227], v[18:21]
	v_mfma_f32_16x16x32_bf16 v[6:9], v[170:173], v[232:235], v[6:9]
	v_mfma_f32_16x16x32_bf16 v[2:5], v[178:181], v[232:235], v[2:5]
	s_setprio 0
	s_barrier
	v_add_u32_e32 v136, 0x18000, v147
	ds_read_b128 v[166:169], v136
	ds_read_b128 v[170:173], v136 offset:1024
	ds_read_b128 v[174:177], v136 offset:2048
	ds_read_b128 v[178:181], v136 offset:3072
	ds_read_b128 v[202:205], v165 offset:32768
	ds_read_b128 v[208:211], v165 offset:33792
	ds_read_b128 v[212:215], v165 offset:34816
	ds_read_b128 v[216:219], v165 offset:35840
	ds_read_b128 v[220:223], v165 offset:36864
	ds_read_b128 v[224:227], v165 offset:37888
	ds_read_b128 v[228:231], v165 offset:38912
	ds_read_b128 v[232:235], v165 offset:39936
	v_lshl_add_u64 v[136:137], s[76:77], 0, v[0:1]
	s_add_i32 m0, s94, 0x0
	v_lshl_add_u64 v[144:145], s[76:77], 0, v[130:131]
	global_load_lds_dwordx4 v[136:137], off
	s_add_i32 m0, s94, 0x2000
	s_nop 0
	global_load_lds_dwordx4 v[144:145], off
	v_lshl_add_u64 v[182:183], vcc, 0, v[0:1]
	s_add_i32 m0, s93, 0x10000
	v_lshl_add_u64 v[236:237], vcc, 0, v[130:131]
	global_load_lds_dwordx4 v[182:183], off
	s_add_i32 m0, s93, 0x12000
	s_nop 0
	global_load_lds_dwordx4 v[236:237], off
	s_cmp_lt_u32 s82, s59
	s_cselect_b32 s83, 0x80, 0
	s_add_u32 s76, s76, s83
	s_addc_u32 s77, s77, 0
	s_add_u32 vcc_lo, vcc_lo, s83
	s_addc_u32 vcc_hi, vcc_hi, 0
	s_add_i32 s82, s82, 1
	s_waitcnt vmcnt(8)
	s_waitcnt lgkmcnt(0)
	s_barrier
	s_setprio 1
	v_mfma_f32_16x16x32_bf16 v[54:57], v[166:169], v[202:205], v[54:57]
	v_mfma_f32_16x16x32_bf16 v[50:53], v[174:177], v[202:205], v[50:53]
	v_mfma_f32_16x16x32_bf16 v[38:41], v[166:169], v[212:215], v[38:41]
	v_mfma_f32_16x16x32_bf16 v[34:37], v[174:177], v[212:215], v[34:37]
	v_mfma_f32_16x16x32_bf16 v[22:25], v[166:169], v[220:223], v[22:25]
	v_mfma_f32_16x16x32_bf16 v[18:21], v[174:177], v[220:223], v[18:21]
	v_mfma_f32_16x16x32_bf16 v[6:9], v[166:169], v[228:231], v[6:9]
	v_mfma_f32_16x16x32_bf16 v[2:5], v[174:177], v[228:231], v[2:5]
	v_mfma_f32_16x16x32_bf16 v[54:57], v[170:173], v[208:211], v[54:57]
	v_mfma_f32_16x16x32_bf16 v[50:53], v[178:181], v[208:211], v[50:53]
	v_mfma_f32_16x16x32_bf16 v[38:41], v[170:173], v[216:219], v[38:41]
	v_mfma_f32_16x16x32_bf16 v[34:37], v[178:181], v[216:219], v[34:37]
	v_mfma_f32_16x16x32_bf16 v[22:25], v[170:173], v[224:227], v[22:25]
	v_mfma_f32_16x16x32_bf16 v[18:21], v[178:181], v[224:227], v[18:21]
	v_mfma_f32_16x16x32_bf16 v[6:9], v[170:173], v[232:235], v[6:9]
	v_mfma_f32_16x16x32_bf16 v[2:5], v[178:181], v[232:235], v[2:5]
	s_setprio 0
	s_barrier
	s_add_i32 s83, s82, -3
	s_cmp_lt_u32 s83, s79
	s_cbranch_scc0 .Lkq_4_post

; #define PG8_STAGE(bufoff, gbase, voff) do { _Pragma("unroll") for (int _i = 0; _i < 2; ++_i) \
;         __builtin_amdgcn_global_load_lds((const unsigned*)((const char*)(gbase) + (voff)[_i]), (PG8_LAS unsigned*)(lds + (bufoff) + ldsw + _i * 8192), 16, 0, 0); } while (0)
; #define PG8_WAIT_V(n) asm volatile("s_waitcnt vmcnt(" #n ")" ::: "memory")
; #define PG8_BAR __builtin_amdgcn_s_barrier()
; template <class Epi, class Sched, bool ALIGN_EPI = false, bool SP2 = false>
; __device__ __forceinline__ void gemm_phase(PG8_LAS unsigned char* lds, const Gemm g, const Sched& S, const Epi& E) {
;     ...
;         PG8_STAGE(PG8_SB(0, 0), cB, voffB); PG8_STAGE(PG8_SB(0, 1), cB + hstep, voffB); PG8_STAGE(PG8_SA(0, 0), cA, voffA); PG8_STAGE(PG8_SA(0, 1), cA + hstep, voffA);
;         if (wr == 1) PG8_BAR;
;         PG8_WAIT_V(2); PG8_BAR;
;         PG8_STAGE(PG8_SB(1, 0), cB + kstep, voffB); PG8_STAGE(PG8_SA(1, 0), cA + kstep, voffA); PG8_STAGE(PG8_SB(1, 1), cB + hstep + kstep, voffB);
;         PG8_WAIT_V(6); PG8_BAR;
.Lkq_4_post:
	s_mov_b64 s[76:77], s[8:9]
	s_mov_b64 vcc, s[46:47]
	v_lshl_add_u64 v[136:137], vcc, 0, v[0:1]
	s_add_i32 m0, s93, 0x10000
	v_lshl_add_u64 v[144:145], vcc, 0, v[130:131]
	global_load_lds_dwordx4 v[136:137], off
	s_add_i32 m0, s93, 0x12000
	s_nop 0
	global_load_lds_dwordx4 v[144:145], off
	s_add_u32 vcc_lo, vcc_lo, s10
	s_addc_u32 vcc_hi, vcc_hi, 0
	v_lshl_add_u64 v[136:137], vcc, 0, v[0:1]
	s_add_i32 m0, s93, 0x14000
	v_lshl_add_u64 v[144:145], vcc, 0, v[130:131]
	global_load_lds_dwordx4 v[136:137], off
	s_add_i32 m0, s93, 0x16000
	s_nop 0
	global_load_lds_dwordx4 v[144:145], off
	v_lshl_add_u64 v[136:137], s[76:77], 0, v[0:1]
	s_add_i32 m0, s94, 0x0
	v_lshl_add_u64 v[144:145], s[76:77], 0, v[130:131]
	global_load_lds_dwordx4 v[136:137], off
	s_add_i32 m0, s94, 0x2000
	s_nop 0
	global_load_lds_dwordx4 v[144:145], off
	s_add_u32 s76, s76, s10
	s_addc_u32 s77, s77, 0
	v_lshl_add_u64 v[136:137], s[76:77], 0, v[0:1]
	s_add_i32 m0, s94, 0x4000
	v_lshl_add_u64 v[144:145], s[76:77], 0, v[130:131]
	global_load_lds_dwordx4 v[136:137], off
	s_add_i32 m0, s94, 0x6000
	s_nop 0
	global_load_lds_dwordx4 v[144:145], off
	s_add_u32 s76, s8, 0x80
	s_addc_u32 s77, s9, 0
	s_add_u32 vcc_lo, s46, 0x80
	s_addc_u32 vcc_hi, s47, 0
	v_lshl_add_u64 v[136:137], vcc, 0, v[0:1]
	s_add_i32 m0, s93, 0x18000
	v_lshl_add_u64 v[144:145], vcc, 0, v[130:131]
	global_load_lds_dwordx4 v[136:137], off
	s_add_i32 m0, s93, 0x1a000
	s_nop 0
	global_load_lds_dwordx4 v[144:145], off
	s_add_u32 vcc_lo, vcc_lo, s10
	s_addc_u32 vcc_hi, vcc_hi, 0
	v_lshl_add_u64 v[136:137], vcc, 0, v[0:1]
	s_add_i32 m0, s93, 0x1c000
	v_lshl_add_u64 v[144:145], vcc, 0, v[130:131]
	global_load_lds_dwordx4 v[136:137], off
	s_add_i32 m0, s93, 0x1e000
	s_nop 0
	global_load_lds_dwordx4 v[144:145], off
	v_lshl_add_u64 v[136:137], s[76:77], 0, v[0:1]
	s_add_i32 m0, s94, 0x8000
	v_lshl_add_u64 v[144:145], s[76:77], 0, v[130:131]
	global_load_lds_dwordx4 v[136:137], off
	s_add_i32 m0, s94, 0xa000
	s_nop 0
	global_load_lds_dwordx4 v[144:145], off
